# all 7 GEMM mainloops: pipelined LDS fragment reads + next-tile loads hoisted into MFMA block; residual epilogues de-serialised (8 loads in flight, counted vmcnt)
# speedup vs baseline: 1.0609x; 1.0216x over previous
.LBB0_26:
	s_mul_i32 s1, s5, s82
	s_add_i32 s1, s1, s63
	s_ashr_i32 s3, s1, 31
	s_lshr_b32 s3, s3, 28
	s_add_i32 s3, s1, s3
	s_ashr_i32 s6, s3, 4
	s_and_b32 s3, s3, -16
	s_sub_i32 s1, s1, s3
	s_lshl_b32 s3, s6, 1
	s_and_b32 s6, s1, 1
	s_or_b32 s3, s6, s3
	v_readlane_b32 s6, v252, 35
	s_sub_i32 s8, 0x7f, s3
	v_readlane_b32 s7, v252, 36
	s_and_b64 s[6:7], s[6:7], exec
	s_cselect_b32 s6, s8, s3
	v_mov_b32_e32 v0, v222
	s_ashr_i32 s7, s6, 31
	v_and_b32_e32 v190, 0xffffff80, v0
	s_lshl_b64 s[6:7], s[6:7], 8
	v_ashrrev_i32_e32 v191, 31, v190
	v_lshl_add_u64 v[190:191], s[6:7], 0, v[190:191]
	s_lshl_b32 s1, s1, 6
	v_and_b32_e32 v185, 64, v0
	v_and_or_b32 v190, v0, 31, v190
	s_and_b32 s1, s1, 0xffffff80
	v_lshrrev_b32_e32 v0, 3, v0
	v_readlane_b32 s6, v252, 31
	s_ashr_i32 s3, s1, 31
	v_and_b32_e32 v0, 4, v0
	v_lshlrev_b64 v[190:191], 12, v[190:191]
	v_readlane_b32 s7, v252, 32
	v_or3_b32 v192, v0, v185, s1
	v_mov_b32_e32 v193, s3
	v_lshl_add_u64 v[190:191], s[6:7], 0, v[190:191]
	v_lshl_add_u64 v[190:191], v[192:193], 2, v[190:191]
	s_mov_b64 s[98:99], 0x20000
	v_lshl_add_u64 v[192:193], v[190:191], 0, 0
	v_lshl_add_u64 v[220:221], v[190:191], 0, 0
	global_load_dwordx4 v[194:197], v[192:193], off
	global_load_dwordx4 v[198:201], v[192:193], off offset:32
	global_load_dwordx4 v[202:205], v[192:193], off offset:64
	global_load_dwordx4 v[206:209], v[192:193], off offset:96
	global_load_dwordx4 v[216:219], v[192:193], off offset:128
	global_load_dwordx4 v[236:239], v[192:193], off offset:160
	global_load_dwordx4 v[240:243], v[192:193], off offset:192
	global_load_dwordx4 v[244:247], v[192:193], off offset:224
	s_waitcnt vmcnt(7)
	v_pk_fma_f32 v[114:115], v[114:115], 0.5, v[194:195] op_sel_hi:[1,0,1]
	v_pk_fma_f32 v[116:117], v[116:117], 0.5, v[196:197] op_sel_hi:[1,0,1]
	global_store_dwordx4 v[220:221], v[114:117], off
	v_lshl_add_u64 v[192:193], v[192:193], 0, s[98:99]
	global_load_dwordx4 v[194:197], v[192:193], off
	s_waitcnt vmcnt(8)
	v_pk_fma_f32 v[118:119], v[118:119], 0.5, v[198:199] op_sel_hi:[1,0,1]
	v_pk_fma_f32 v[120:121], v[120:121], 0.5, v[200:201] op_sel_hi:[1,0,1]
	global_store_dwordx4 v[220:221], v[118:121], off offset:32
	global_load_dwordx4 v[198:201], v[192:193], off offset:32
	s_waitcnt vmcnt(9)
	v_pk_fma_f32 v[122:123], v[122:123], 0.5, v[202:203] op_sel_hi:[1,0,1]
	v_pk_fma_f32 v[124:125], v[124:125], 0.5, v[204:205] op_sel_hi:[1,0,1]
	global_store_dwordx4 v[220:221], v[122:125], off offset:64
	global_load_dwordx4 v[202:205], v[192:193], off offset:64
	s_waitcnt vmcnt(10)
	v_pk_fma_f32 v[126:127], v[126:127], 0.5, v[206:207] op_sel_hi:[1,0,1]
	v_pk_fma_f32 v[128:129], v[128:129], 0.5, v[208:209] op_sel_hi:[1,0,1]
	global_store_dwordx4 v[220:221], v[126:129], off offset:96
	global_load_dwordx4 v[206:209], v[192:193], off offset:96
	s_waitcnt vmcnt(11)
	v_pk_fma_f32 v[98:99], v[98:99], 0.5, v[216:217] op_sel_hi:[1,0,1]
	v_pk_fma_f32 v[100:101], v[100:101], 0.5, v[218:219] op_sel_hi:[1,0,1]
	global_store_dwordx4 v[220:221], v[98:101], off offset:128
	global_load_dwordx4 v[216:219], v[192:193], off offset:128
	s_waitcnt vmcnt(12)
	v_pk_fma_f32 v[102:103], v[102:103], 0.5, v[236:237] op_sel_hi:[1,0,1]
	v_pk_fma_f32 v[104:105], v[104:105], 0.5, v[238:239] op_sel_hi:[1,0,1]
	global_store_dwordx4 v[220:221], v[102:105], off offset:160
	global_load_dwordx4 v[236:239], v[192:193], off offset:160
	s_waitcnt vmcnt(13)
	v_pk_fma_f32 v[106:107], v[106:107], 0.5, v[240:241] op_sel_hi:[1,0,1]
	v_pk_fma_f32 v[108:109], v[108:109], 0.5, v[242:243] op_sel_hi:[1,0,1]
	global_store_dwordx4 v[220:221], v[106:109], off offset:192
	global_load_dwordx4 v[240:243], v[192:193], off offset:192
	s_waitcnt vmcnt(14)
	v_pk_fma_f32 v[110:111], v[110:111], 0.5, v[244:245] op_sel_hi:[1,0,1]
	v_pk_fma_f32 v[112:113], v[112:113], 0.5, v[246:247] op_sel_hi:[1,0,1]
	global_store_dwordx4 v[220:221], v[110:113], off offset:224
	global_load_dwordx4 v[244:247], v[192:193], off offset:224
	s_waitcnt vmcnt(14)
	v_pk_fma_f32 v[82:83], v[82:83], 0.5, v[194:195] op_sel_hi:[1,0,1]
	v_pk_fma_f32 v[84:85], v[84:85], 0.5, v[196:197] op_sel_hi:[1,0,1]
	v_lshl_add_u64 v[220:221], v[220:221], 0, s[98:99]
	global_store_dwordx4 v[220:221], v[82:85], off
	v_lshl_add_u64 v[192:193], v[192:193], 0, s[98:99]
	global_load_dwordx4 v[194:197], v[192:193], off
	s_waitcnt vmcnt(14)
	v_pk_fma_f32 v[86:87], v[86:87], 0.5, v[198:199] op_sel_hi:[1,0,1]
	v_pk_fma_f32 v[88:89], v[88:89], 0.5, v[200:201] op_sel_hi:[1,0,1]
	global_store_dwordx4 v[220:221], v[86:89], off offset:32
	global_load_dwordx4 v[198:201], v[192:193], off offset:32
	s_waitcnt vmcnt(14)
	v_pk_fma_f32 v[90:91], v[90:91], 0.5, v[202:203] op_sel_hi:[1,0,1]
	v_pk_fma_f32 v[92:93], v[92:93], 0.5, v[204:205] op_sel_hi:[1,0,1]
	global_store_dwordx4 v[220:221], v[90:93], off offset:64
	global_load_dwordx4 v[202:205], v[192:193], off offset:64
	s_waitcnt vmcnt(14)
	v_pk_fma_f32 v[94:95], v[94:95], 0.5, v[206:207] op_sel_hi:[1,0,1]
	v_pk_fma_f32 v[96:97], v[96:97], 0.5, v[208:209] op_sel_hi:[1,0,1]
	global_store_dwordx4 v[220:221], v[94:97], off offset:96
	global_load_dwordx4 v[206:209], v[192:193], off offset:96
	s_waitcnt vmcnt(14)
	v_pk_fma_f32 v[66:67], v[66:67], 0.5, v[216:217] op_sel_hi:[1,0,1]
	v_pk_fma_f32 v[68:69], v[68:69], 0.5, v[218:219] op_sel_hi:[1,0,1]
	global_store_dwordx4 v[220:221], v[66:69], off offset:128
	global_load_dwordx4 v[216:219], v[192:193], off offset:128
	s_waitcnt vmcnt(14)
	v_pk_fma_f32 v[70:71], v[70:71], 0.5, v[236:237] op_sel_hi:[1,0,1]
	v_pk_fma_f32 v[72:73], v[72:73], 0.5, v[238:239] op_sel_hi:[1,0,1]
	global_store_dwordx4 v[220:221], v[70:73], off offset:160
	global_load_dwordx4 v[236:239], v[192:193], off offset:160
	s_waitcnt vmcnt(14)
	v_pk_fma_f32 v[74:75], v[74:75], 0.5, v[240:241] op_sel_hi:[1,0,1]
	v_pk_fma_f32 v[76:77], v[76:77], 0.5, v[242:243] op_sel_hi:[1,0,1]
	global_store_dwordx4 v[220:221], v[74:77], off offset:192
	global_load_dwordx4 v[240:243], v[192:193], off offset:192
	s_waitcnt vmcnt(14)
	v_pk_fma_f32 v[78:79], v[78:79], 0.5, v[244:245] op_sel_hi:[1,0,1]
	v_pk_fma_f32 v[80:81], v[80:81], 0.5, v[246:247] op_sel_hi:[1,0,1]
	global_store_dwordx4 v[220:221], v[78:81], off offset:224
	global_load_dwordx4 v[244:247], v[192:193], off offset:224
	s_waitcnt vmcnt(14)
	v_pk_fma_f32 v[50:51], v[50:51], 0.5, v[194:195] op_sel_hi:[1,0,1]
	v_pk_fma_f32 v[52:53], v[52:53], 0.5, v[196:197] op_sel_hi:[1,0,1]
	v_lshl_add_u64 v[220:221], v[220:221], 0, s[98:99]
	global_store_dwordx4 v[220:221], v[50:53], off
	v_lshl_add_u64 v[192:193], v[192:193], 0, s[98:99]
	global_load_dwordx4 v[194:197], v[192:193], off
	s_waitcnt vmcnt(14)
	v_pk_fma_f32 v[54:55], v[54:55], 0.5, v[198:199] op_sel_hi:[1,0,1]
	v_pk_fma_f32 v[56:57], v[56:57], 0.5, v[200:201] op_sel_hi:[1,0,1]
	global_store_dwordx4 v[220:221], v[54:57], off offset:32
	global_load_dwordx4 v[198:201], v[192:193], off offset:32
	s_waitcnt vmcnt(14)
	v_pk_fma_f32 v[58:59], v[58:59], 0.5, v[202:203] op_sel_hi:[1,0,1]
	v_pk_fma_f32 v[60:61], v[60:61], 0.5, v[204:205] op_sel_hi:[1,0,1]
	global_store_dwordx4 v[220:221], v[58:61], off offset:64
	global_load_dwordx4 v[202:205], v[192:193], off offset:64
	s_waitcnt vmcnt(14)
	v_pk_fma_f32 v[62:63], v[62:63], 0.5, v[206:207] op_sel_hi:[1,0,1]
	v_pk_fma_f32 v[64:65], v[64:65], 0.5, v[208:209] op_sel_hi:[1,0,1]
	global_store_dwordx4 v[220:221], v[62:65], off offset:96
	global_load_dwordx4 v[206:209], v[192:193], off offset:96
	s_waitcnt vmcnt(14)
	v_pk_fma_f32 v[34:35], v[34:35], 0.5, v[216:217] op_sel_hi:[1,0,1]
	v_pk_fma_f32 v[36:37], v[36:37], 0.5, v[218:219] op_sel_hi:[1,0,1]
	global_store_dwordx4 v[220:221], v[34:37], off offset:128
	global_load_dwordx4 v[216:219], v[192:193], off offset:128
	s_waitcnt vmcnt(14)
	v_pk_fma_f32 v[38:39], v[38:39], 0.5, v[236:237] op_sel_hi:[1,0,1]
	v_pk_fma_f32 v[40:41], v[40:41], 0.5, v[238:239] op_sel_hi:[1,0,1]
	global_store_dwordx4 v[220:221], v[38:41], off offset:160
	global_load_dwordx4 v[236:239], v[192:193], off offset:160
	s_waitcnt vmcnt(14)
	v_pk_fma_f32 v[42:43], v[42:43], 0.5, v[240:241] op_sel_hi:[1,0,1]
	v_pk_fma_f32 v[44:45], v[44:45], 0.5, v[242:243] op_sel_hi:[1,0,1]
	global_store_dwordx4 v[220:221], v[42:45], off offset:192
	global_load_dwordx4 v[240:243], v[192:193], off offset:192
	s_waitcnt vmcnt(14)
	v_pk_fma_f32 v[46:47], v[46:47], 0.5, v[244:245] op_sel_hi:[1,0,1]
	v_pk_fma_f32 v[48:49], v[48:49], 0.5, v[246:247] op_sel_hi:[1,0,1]
	global_store_dwordx4 v[220:221], v[46:49], off offset:224
	global_load_dwordx4 v[244:247], v[192:193], off offset:224
	s_waitcnt vmcnt(14)
	v_pk_fma_f32 v[18:19], v[18:19], 0.5, v[194:195] op_sel_hi:[1,0,1]
	v_pk_fma_f32 v[20:21], v[20:21], 0.5, v[196:197] op_sel_hi:[1,0,1]
	v_lshl_add_u64 v[220:221], v[220:221], 0, s[98:99]
	global_store_dwordx4 v[220:221], v[18:21], off
	s_waitcnt vmcnt(13)
	v_pk_fma_f32 v[22:23], v[22:23], 0.5, v[198:199] op_sel_hi:[1,0,1]
	v_pk_fma_f32 v[24:25], v[24:25], 0.5, v[200:201] op_sel_hi:[1,0,1]
	global_store_dwordx4 v[220:221], v[22:25], off offset:32
	s_waitcnt vmcnt(12)
	v_pk_fma_f32 v[26:27], v[26:27], 0.5, v[202:203] op_sel_hi:[1,0,1]
	v_pk_fma_f32 v[28:29], v[28:29], 0.5, v[204:205] op_sel_hi:[1,0,1]
	global_store_dwordx4 v[220:221], v[26:29], off offset:64
	s_waitcnt vmcnt(11)
	v_pk_fma_f32 v[30:31], v[30:31], 0.5, v[206:207] op_sel_hi:[1,0,1]
	v_pk_fma_f32 v[32:33], v[32:33], 0.5, v[208:209] op_sel_hi:[1,0,1]
	global_store_dwordx4 v[220:221], v[30:33], off offset:96
	s_waitcnt vmcnt(10)
	v_pk_fma_f32 v[2:3], v[2:3], 0.5, v[216:217] op_sel_hi:[1,0,1]
	v_pk_fma_f32 v[4:5], v[4:5], 0.5, v[218:219] op_sel_hi:[1,0,1]
	global_store_dwordx4 v[220:221], v[2:5], off offset:128
	s_waitcnt vmcnt(9)
	v_pk_fma_f32 v[6:7], v[6:7], 0.5, v[236:237] op_sel_hi:[1,0,1]
	v_pk_fma_f32 v[8:9], v[8:9], 0.5, v[238:239] op_sel_hi:[1,0,1]
	global_store_dwordx4 v[220:221], v[6:9], off offset:160
	s_waitcnt vmcnt(8)
	v_pk_fma_f32 v[10:11], v[10:11], 0.5, v[240:241] op_sel_hi:[1,0,1]
	v_pk_fma_f32 v[12:13], v[12:13], 0.5, v[242:243] op_sel_hi:[1,0,1]
	global_store_dwordx4 v[220:221], v[10:13], off offset:192
	s_waitcnt vmcnt(7)
	v_pk_fma_f32 v[14:15], v[14:15], 0.5, v[244:245] op_sel_hi:[1,0,1]
	v_pk_fma_f32 v[16:17], v[16:17], 0.5, v[246:247] op_sel_hi:[1,0,1]
	global_store_dwordx4 v[220:221], v[14:17], off offset:224
	s_mov_b32 s3, 0
	s_add_i32 s5, s5, 1
	v_mov_b32_e32 v114, 0
	v_mov_b32_e32 v115, 0
	v_mov_b32_e32 v116, 0
	v_mov_b32_e32 v117, 0
	v_mov_b32_e32 v118, 0
	v_mov_b32_e32 v119, 0
	v_mov_b32_e32 v120, 0
	v_mov_b32_e32 v121, 0
	v_mov_b32_e32 v122, 0
	v_mov_b32_e32 v123, 0
	v_mov_b32_e32 v124, 0
	v_mov_b32_e32 v125, 0
	v_mov_b32_e32 v126, 0
	v_mov_b32_e32 v127, 0
	v_mov_b32_e32 v128, 0
	v_mov_b32_e32 v129, 0
	v_mov_b32_e32 v98, 0
	v_mov_b32_e32 v99, 0
	v_mov_b32_e32 v100, 0
	v_mov_b32_e32 v101, 0
	v_mov_b32_e32 v102, 0
	v_mov_b32_e32 v103, 0
	v_mov_b32_e32 v104, 0
	v_mov_b32_e32 v105, 0
	v_mov_b32_e32 v106, 0
	v_mov_b32_e32 v107, 0
	v_mov_b32_e32 v108, 0
	v_mov_b32_e32 v109, 0
	v_mov_b32_e32 v110, 0
	v_mov_b32_e32 v111, 0
	v_mov_b32_e32 v112, 0
	v_mov_b32_e32 v113, 0
	v_mov_b32_e32 v82, 0
	v_mov_b32_e32 v83, 0
	v_mov_b32_e32 v84, 0
	v_mov_b32_e32 v85, 0
	v_mov_b32_e32 v86, 0
	v_mov_b32_e32 v87, 0
	v_mov_b32_e32 v88, 0
	v_mov_b32_e32 v89, 0
	v_mov_b32_e32 v90, 0
	v_mov_b32_e32 v91, 0
	v_mov_b32_e32 v92, 0
	v_mov_b32_e32 v93, 0
	v_mov_b32_e32 v94, 0
	v_mov_b32_e32 v95, 0
	v_mov_b32_e32 v96, 0
	v_mov_b32_e32 v97, 0
	v_mov_b32_e32 v66, 0
	v_mov_b32_e32 v67, 0
	v_mov_b32_e32 v68, 0
	v_mov_b32_e32 v69, 0
	v_mov_b32_e32 v70, 0
	v_mov_b32_e32 v71, 0
	v_mov_b32_e32 v72, 0
	v_mov_b32_e32 v73, 0
	v_mov_b32_e32 v74, 0
	v_mov_b32_e32 v75, 0
	v_mov_b32_e32 v76, 0
	v_mov_b32_e32 v77, 0
	v_mov_b32_e32 v78, 0
	v_mov_b32_e32 v79, 0
	v_mov_b32_e32 v80, 0
	v_mov_b32_e32 v81, 0
	v_mov_b32_e32 v50, 0
	v_mov_b32_e32 v51, 0
	v_mov_b32_e32 v52, 0
	v_mov_b32_e32 v53, 0
	v_mov_b32_e32 v54, 0
	v_mov_b32_e32 v55, 0
	v_mov_b32_e32 v56, 0
	v_mov_b32_e32 v57, 0
	v_mov_b32_e32 v58, 0
	v_mov_b32_e32 v59, 0
	v_mov_b32_e32 v60, 0
	v_mov_b32_e32 v61, 0
	v_mov_b32_e32 v62, 0
	v_mov_b32_e32 v63, 0
	v_mov_b32_e32 v64, 0
	v_mov_b32_e32 v65, 0
	v_mov_b32_e32 v34, 0
	v_mov_b32_e32 v35, 0
	v_mov_b32_e32 v36, 0
	v_mov_b32_e32 v37, 0
	v_mov_b32_e32 v38, 0
	v_mov_b32_e32 v39, 0
	v_mov_b32_e32 v40, 0
	v_mov_b32_e32 v41, 0
	v_mov_b32_e32 v42, 0
	v_mov_b32_e32 v43, 0
	v_mov_b32_e32 v44, 0
	v_mov_b32_e32 v45, 0
	v_mov_b32_e32 v46, 0
	v_mov_b32_e32 v47, 0
	v_mov_b32_e32 v48, 0
	v_mov_b32_e32 v49, 0
	v_mov_b32_e32 v18, 0
	v_mov_b32_e32 v19, 0
	v_mov_b32_e32 v20, 0
	v_mov_b32_e32 v21, 0
	v_mov_b32_e32 v22, 0
	v_mov_b32_e32 v23, 0
	v_mov_b32_e32 v24, 0
	v_mov_b32_e32 v25, 0
	v_mov_b32_e32 v26, 0
	v_mov_b32_e32 v27, 0
	v_mov_b32_e32 v28, 0
	v_mov_b32_e32 v29, 0
	v_mov_b32_e32 v30, 0
	v_mov_b32_e32 v31, 0
	v_mov_b32_e32 v32, 0
	v_mov_b32_e32 v33, 0
	v_mov_b32_e32 v2, 0
	v_mov_b32_e32 v3, 0
	v_mov_b32_e32 v4, 0
	v_mov_b32_e32 v5, 0
	v_mov_b32_e32 v6, 0
	v_mov_b32_e32 v7, 0
	v_mov_b32_e32 v8, 0
	v_mov_b32_e32 v9, 0
	v_mov_b32_e32 v10, 0
	v_mov_b32_e32 v11, 0
	v_mov_b32_e32 v12, 0
	v_mov_b32_e32 v13, 0
	v_mov_b32_e32 v14, 0
	v_mov_b32_e32 v15, 0
	v_mov_b32_e32 v16, 0
	v_mov_b32_e32 v17, 0
	s_cmp_lt_i32 s5, s4
	s_cbranch_scc1 .LBB0_22

.LBB0_68:
	s_mul_i32 s1, s7, s82
	s_add_i32 s1, s1, s63
	s_ashr_i32 s3, s1, 31
	s_lshr_b32 s3, s3, 28
	s_add_i32 s3, s1, s3
	s_ashr_i32 s4, s3, 4
	s_and_b32 s3, s3, -16
	s_sub_i32 s1, s1, s3
	s_lshl_b32 s3, s4, 1
	s_and_b32 s4, s1, 1
	s_or_b32 s3, s4, s3
	v_readlane_b32 s4, v252, 35
	s_sub_i32 s8, 0x7f, s3
	v_readlane_b32 s5, v252, 36
	s_and_b64 s[4:5], s[4:5], exec
	s_cselect_b32 s4, s8, s3
	v_mov_b32_e32 v0, v222
	s_ashr_i32 s5, s4, 31
	v_and_b32_e32 v190, 0xffffff80, v0
	s_lshl_b64 s[4:5], s[4:5], 8
	v_ashrrev_i32_e32 v191, 31, v190
	v_lshl_add_u64 v[190:191], s[4:5], 0, v[190:191]
	s_lshl_b32 s1, s1, 6
	v_and_b32_e32 v185, 64, v0
	v_and_or_b32 v190, v0, 31, v190
	s_and_b32 s1, s1, 0xffffff80
	v_lshrrev_b32_e32 v0, 3, v0
	v_readlane_b32 s4, v252, 31
	s_ashr_i32 s3, s1, 31
	v_and_b32_e32 v0, 4, v0
	v_lshlrev_b64 v[190:191], 12, v[190:191]
	v_readlane_b32 s5, v252, 32
	v_or3_b32 v192, v0, v185, s1
	v_mov_b32_e32 v193, s3
	v_lshl_add_u64 v[190:191], s[4:5], 0, v[190:191]
	v_lshl_add_u64 v[190:191], v[192:193], 2, v[190:191]
	s_mov_b64 s[98:99], 0x20000
	v_lshl_add_u64 v[192:193], v[190:191], 0, 0
	v_lshl_add_u64 v[220:221], v[190:191], 0, 0
	global_load_dwordx4 v[194:197], v[192:193], off
	global_load_dwordx4 v[198:201], v[192:193], off offset:32
	global_load_dwordx4 v[202:205], v[192:193], off offset:64
	global_load_dwordx4 v[206:209], v[192:193], off offset:96
	global_load_dwordx4 v[216:219], v[192:193], off offset:128
	global_load_dwordx4 v[236:239], v[192:193], off offset:160
	global_load_dwordx4 v[240:243], v[192:193], off offset:192
	global_load_dwordx4 v[244:247], v[192:193], off offset:224
	s_waitcnt vmcnt(7)
	v_pk_add_f32 v[114:115], v[114:115], v[194:195]
	v_pk_add_f32 v[116:117], v[116:117], v[196:197]
	global_store_dwordx4 v[220:221], v[114:117], off
	v_lshl_add_u64 v[192:193], v[192:193], 0, s[98:99]
	global_load_dwordx4 v[194:197], v[192:193], off
	s_waitcnt vmcnt(8)
	v_pk_add_f32 v[118:119], v[118:119], v[198:199]
	v_pk_add_f32 v[120:121], v[120:121], v[200:201]
	global_store_dwordx4 v[220:221], v[118:121], off offset:32
	global_load_dwordx4 v[198:201], v[192:193], off offset:32
	s_waitcnt vmcnt(9)
	v_pk_add_f32 v[122:123], v[122:123], v[202:203]
	v_pk_add_f32 v[124:125], v[124:125], v[204:205]
	global_store_dwordx4 v[220:221], v[122:125], off offset:64
	global_load_dwordx4 v[202:205], v[192:193], off offset:64
	s_waitcnt vmcnt(10)
	v_pk_add_f32 v[126:127], v[126:127], v[206:207]
	v_pk_add_f32 v[128:129], v[128:129], v[208:209]
	global_store_dwordx4 v[220:221], v[126:129], off offset:96
	global_load_dwordx4 v[206:209], v[192:193], off offset:96
	s_waitcnt vmcnt(11)
	v_pk_add_f32 v[98:99], v[98:99], v[216:217]
	v_pk_add_f32 v[100:101], v[100:101], v[218:219]
	global_store_dwordx4 v[220:221], v[98:101], off offset:128
	global_load_dwordx4 v[216:219], v[192:193], off offset:128
	s_waitcnt vmcnt(12)
	v_pk_add_f32 v[102:103], v[102:103], v[236:237]
	v_pk_add_f32 v[104:105], v[104:105], v[238:239]
	global_store_dwordx4 v[220:221], v[102:105], off offset:160
	global_load_dwordx4 v[236:239], v[192:193], off offset:160
	s_waitcnt vmcnt(13)
	v_pk_add_f32 v[106:107], v[106:107], v[240:241]
	v_pk_add_f32 v[108:109], v[108:109], v[242:243]
	global_store_dwordx4 v[220:221], v[106:109], off offset:192
	global_load_dwordx4 v[240:243], v[192:193], off offset:192
	s_waitcnt vmcnt(14)
	v_pk_add_f32 v[110:111], v[110:111], v[244:245]
	v_pk_add_f32 v[112:113], v[112:113], v[246:247]
	global_store_dwordx4 v[220:221], v[110:113], off offset:224
	global_load_dwordx4 v[244:247], v[192:193], off offset:224
	s_waitcnt vmcnt(14)
	v_pk_add_f32 v[82:83], v[82:83], v[194:195]
	v_pk_add_f32 v[84:85], v[84:85], v[196:197]
	v_lshl_add_u64 v[220:221], v[220:221], 0, s[98:99]
	global_store_dwordx4 v[220:221], v[82:85], off
	v_lshl_add_u64 v[192:193], v[192:193], 0, s[98:99]
	global_load_dwordx4 v[194:197], v[192:193], off
	s_waitcnt vmcnt(14)
	v_pk_add_f32 v[86:87], v[86:87], v[198:199]
	v_pk_add_f32 v[88:89], v[88:89], v[200:201]
	global_store_dwordx4 v[220:221], v[86:89], off offset:32
	global_load_dwordx4 v[198:201], v[192:193], off offset:32
	s_waitcnt vmcnt(14)
	v_pk_add_f32 v[90:91], v[90:91], v[202:203]
	v_pk_add_f32 v[92:93], v[92:93], v[204:205]
	global_store_dwordx4 v[220:221], v[90:93], off offset:64
	global_load_dwordx4 v[202:205], v[192:193], off offset:64
	s_waitcnt vmcnt(14)
	v_pk_add_f32 v[94:95], v[94:95], v[206:207]
	v_pk_add_f32 v[96:97], v[96:97], v[208:209]
	global_store_dwordx4 v[220:221], v[94:97], off offset:96
	global_load_dwordx4 v[206:209], v[192:193], off offset:96
	s_waitcnt vmcnt(14)
	v_pk_add_f32 v[66:67], v[66:67], v[216:217]
	v_pk_add_f32 v[68:69], v[68:69], v[218:219]
	global_store_dwordx4 v[220:221], v[66:69], off offset:128
	global_load_dwordx4 v[216:219], v[192:193], off offset:128
	s_waitcnt vmcnt(14)
	v_pk_add_f32 v[70:71], v[70:71], v[236:237]
	v_pk_add_f32 v[72:73], v[72:73], v[238:239]
	global_store_dwordx4 v[220:221], v[70:73], off offset:160
	global_load_dwordx4 v[236:239], v[192:193], off offset:160
	s_waitcnt vmcnt(14)
	v_pk_add_f32 v[74:75], v[74:75], v[240:241]
	v_pk_add_f32 v[76:77], v[76:77], v[242:243]
	global_store_dwordx4 v[220:221], v[74:77], off offset:192
	global_load_dwordx4 v[240:243], v[192:193], off offset:192
	s_waitcnt vmcnt(14)
	v_pk_add_f32 v[78:79], v[78:79], v[244:245]
	v_pk_add_f32 v[80:81], v[80:81], v[246:247]
	global_store_dwordx4 v[220:221], v[78:81], off offset:224
	global_load_dwordx4 v[244:247], v[192:193], off offset:224
	s_waitcnt vmcnt(14)
	v_pk_add_f32 v[50:51], v[50:51], v[194:195]
	v_pk_add_f32 v[52:53], v[52:53], v[196:197]
	v_lshl_add_u64 v[220:221], v[220:221], 0, s[98:99]
	global_store_dwordx4 v[220:221], v[50:53], off
	v_lshl_add_u64 v[192:193], v[192:193], 0, s[98:99]
	global_load_dwordx4 v[194:197], v[192:193], off
	s_waitcnt vmcnt(14)
	v_pk_add_f32 v[54:55], v[54:55], v[198:199]
	v_pk_add_f32 v[56:57], v[56:57], v[200:201]
	global_store_dwordx4 v[220:221], v[54:57], off offset:32
	global_load_dwordx4 v[198:201], v[192:193], off offset:32
	s_waitcnt vmcnt(14)
	v_pk_add_f32 v[58:59], v[58:59], v[202:203]
	v_pk_add_f32 v[60:61], v[60:61], v[204:205]
	global_store_dwordx4 v[220:221], v[58:61], off offset:64
	global_load_dwordx4 v[202:205], v[192:193], off offset:64
	s_waitcnt vmcnt(14)
	v_pk_add_f32 v[62:63], v[62:63], v[206:207]
	v_pk_add_f32 v[64:65], v[64:65], v[208:209]
	global_store_dwordx4 v[220:221], v[62:65], off offset:96
	global_load_dwordx4 v[206:209], v[192:193], off offset:96
	s_waitcnt vmcnt(14)
	v_pk_add_f32 v[34:35], v[34:35], v[216:217]
	v_pk_add_f32 v[36:37], v[36:37], v[218:219]
	global_store_dwordx4 v[220:221], v[34:37], off offset:128
	global_load_dwordx4 v[216:219], v[192:193], off offset:128
	s_waitcnt vmcnt(14)
	v_pk_add_f32 v[38:39], v[38:39], v[236:237]
	v_pk_add_f32 v[40:41], v[40:41], v[238:239]
	global_store_dwordx4 v[220:221], v[38:41], off offset:160
	global_load_dwordx4 v[236:239], v[192:193], off offset:160
	s_waitcnt vmcnt(14)
	v_pk_add_f32 v[42:43], v[42:43], v[240:241]
	v_pk_add_f32 v[44:45], v[44:45], v[242:243]
	global_store_dwordx4 v[220:221], v[42:45], off offset:192
	global_load_dwordx4 v[240:243], v[192:193], off offset:192
	s_waitcnt vmcnt(14)
	v_pk_add_f32 v[46:47], v[46:47], v[244:245]
	v_pk_add_f32 v[48:49], v[48:49], v[246:247]
	global_store_dwordx4 v[220:221], v[46:49], off offset:224
	global_load_dwordx4 v[244:247], v[192:193], off offset:224
	s_waitcnt vmcnt(14)
	v_pk_add_f32 v[18:19], v[18:19], v[194:195]
	v_pk_add_f32 v[20:21], v[20:21], v[196:197]
	v_lshl_add_u64 v[220:221], v[220:221], 0, s[98:99]
	global_store_dwordx4 v[220:221], v[18:21], off
	s_waitcnt vmcnt(13)
	v_pk_add_f32 v[22:23], v[22:23], v[198:199]
	v_pk_add_f32 v[24:25], v[24:25], v[200:201]
	global_store_dwordx4 v[220:221], v[22:25], off offset:32
	s_waitcnt vmcnt(12)
	v_pk_add_f32 v[26:27], v[26:27], v[202:203]
	v_pk_add_f32 v[28:29], v[28:29], v[204:205]
	global_store_dwordx4 v[220:221], v[26:29], off offset:64
	s_waitcnt vmcnt(11)
	v_pk_add_f32 v[30:31], v[30:31], v[206:207]
	v_pk_add_f32 v[32:33], v[32:33], v[208:209]
	global_store_dwordx4 v[220:221], v[30:33], off offset:96
	s_waitcnt vmcnt(10)
	v_pk_add_f32 v[2:3], v[2:3], v[216:217]
	v_pk_add_f32 v[4:5], v[4:5], v[218:219]
	global_store_dwordx4 v[220:221], v[2:5], off offset:128
	s_waitcnt vmcnt(9)
	v_pk_add_f32 v[6:7], v[6:7], v[236:237]
	v_pk_add_f32 v[8:9], v[8:9], v[238:239]
	global_store_dwordx4 v[220:221], v[6:9], off offset:160
	s_waitcnt vmcnt(8)
	v_pk_add_f32 v[10:11], v[10:11], v[240:241]
	v_pk_add_f32 v[12:13], v[12:13], v[242:243]
	global_store_dwordx4 v[220:221], v[10:13], off offset:192
	s_waitcnt vmcnt(7)
	v_pk_add_f32 v[14:15], v[14:15], v[244:245]
	v_pk_add_f32 v[16:17], v[16:17], v[246:247]
	global_store_dwordx4 v[220:221], v[14:17], off offset:224
	s_mov_b32 s3, 0
	s_add_i32 s7, s7, 1
	v_mov_b32_e32 v114, 0
	v_mov_b32_e32 v115, 0
	v_mov_b32_e32 v116, 0
	v_mov_b32_e32 v117, 0
	v_mov_b32_e32 v118, 0
	v_mov_b32_e32 v119, 0
	v_mov_b32_e32 v120, 0
	v_mov_b32_e32 v121, 0
	v_mov_b32_e32 v122, 0
	v_mov_b32_e32 v123, 0
	v_mov_b32_e32 v124, 0
	v_mov_b32_e32 v125, 0
	v_mov_b32_e32 v126, 0
	v_mov_b32_e32 v127, 0
	v_mov_b32_e32 v128, 0
	v_mov_b32_e32 v129, 0
	v_mov_b32_e32 v98, 0
	v_mov_b32_e32 v99, 0
	v_mov_b32_e32 v100, 0
	v_mov_b32_e32 v101, 0
	v_mov_b32_e32 v102, 0
	v_mov_b32_e32 v103, 0
	v_mov_b32_e32 v104, 0
	v_mov_b32_e32 v105, 0
	v_mov_b32_e32 v106, 0
	v_mov_b32_e32 v107, 0
	v_mov_b32_e32 v108, 0
	v_mov_b32_e32 v109, 0
	v_mov_b32_e32 v110, 0
	v_mov_b32_e32 v111, 0
	v_mov_b32_e32 v112, 0
	v_mov_b32_e32 v113, 0
	v_mov_b32_e32 v82, 0
	v_mov_b32_e32 v83, 0
	v_mov_b32_e32 v84, 0
	v_mov_b32_e32 v85, 0
	v_mov_b32_e32 v86, 0
	v_mov_b32_e32 v87, 0
	v_mov_b32_e32 v88, 0
	v_mov_b32_e32 v89, 0
	v_mov_b32_e32 v90, 0
	v_mov_b32_e32 v91, 0
	v_mov_b32_e32 v92, 0
	v_mov_b32_e32 v93, 0
	v_mov_b32_e32 v94, 0
	v_mov_b32_e32 v95, 0
	v_mov_b32_e32 v96, 0
	v_mov_b32_e32 v97, 0
	v_mov_b32_e32 v66, 0
	v_mov_b32_e32 v67, 0
	v_mov_b32_e32 v68, 0
	v_mov_b32_e32 v69, 0
	v_mov_b32_e32 v70, 0
	v_mov_b32_e32 v71, 0
	v_mov_b32_e32 v72, 0
	v_mov_b32_e32 v73, 0
	v_mov_b32_e32 v74, 0
	v_mov_b32_e32 v75, 0
	v_mov_b32_e32 v76, 0
	v_mov_b32_e32 v77, 0
	v_mov_b32_e32 v78, 0
	v_mov_b32_e32 v79, 0
	v_mov_b32_e32 v80, 0
	v_mov_b32_e32 v81, 0
	v_mov_b32_e32 v50, 0
	v_mov_b32_e32 v51, 0
	v_mov_b32_e32 v52, 0
	v_mov_b32_e32 v53, 0
	v_mov_b32_e32 v54, 0
	v_mov_b32_e32 v55, 0
	v_mov_b32_e32 v56, 0
	v_mov_b32_e32 v57, 0
	v_mov_b32_e32 v58, 0
	v_mov_b32_e32 v59, 0
	v_mov_b32_e32 v60, 0
	v_mov_b32_e32 v61, 0
	v_mov_b32_e32 v62, 0
	v_mov_b32_e32 v63, 0
	v_mov_b32_e32 v64, 0
	v_mov_b32_e32 v65, 0
	v_mov_b32_e32 v34, 0
	v_mov_b32_e32 v35, 0
	v_mov_b32_e32 v36, 0
	v_mov_b32_e32 v37, 0
	v_mov_b32_e32 v38, 0
	v_mov_b32_e32 v39, 0
	v_mov_b32_e32 v40, 0
	v_mov_b32_e32 v41, 0
	v_mov_b32_e32 v42, 0
	v_mov_b32_e32 v43, 0
	v_mov_b32_e32 v44, 0
	v_mov_b32_e32 v45, 0
	v_mov_b32_e32 v46, 0
	v_mov_b32_e32 v47, 0
	v_mov_b32_e32 v48, 0
	v_mov_b32_e32 v49, 0
	v_mov_b32_e32 v18, 0
	v_mov_b32_e32 v19, 0
	v_mov_b32_e32 v20, 0
	v_mov_b32_e32 v21, 0
	v_mov_b32_e32 v22, 0
	v_mov_b32_e32 v23, 0
	v_mov_b32_e32 v24, 0
	v_mov_b32_e32 v25, 0
	v_mov_b32_e32 v26, 0
	v_mov_b32_e32 v27, 0
	v_mov_b32_e32 v28, 0
	v_mov_b32_e32 v29, 0
	v_mov_b32_e32 v30, 0
	v_mov_b32_e32 v31, 0
	v_mov_b32_e32 v32, 0
	v_mov_b32_e32 v33, 0
	v_mov_b32_e32 v2, 0
	v_mov_b32_e32 v3, 0
	v_mov_b32_e32 v4, 0
	v_mov_b32_e32 v5, 0
	v_mov_b32_e32 v6, 0
	v_mov_b32_e32 v7, 0
	v_mov_b32_e32 v8, 0
	v_mov_b32_e32 v9, 0
	v_mov_b32_e32 v10, 0
	v_mov_b32_e32 v11, 0
	v_mov_b32_e32 v12, 0
	v_mov_b32_e32 v13, 0
	v_mov_b32_e32 v14, 0
	v_mov_b32_e32 v15, 0
	v_mov_b32_e32 v16, 0
	v_mov_b32_e32 v17, 0
	s_cmp_ge_i32 s7, s6
	s_cbranch_scc0 .LBB0_64

.LcL_92:
	s_waitcnt lgkmcnt(0)
	s_barrier
	s_setprio 2
	ds_read_b128 v[190:193], v181 offset:36864
	ds_read_b128 v[194:197], v181 offset:41472
	ds_read_b128 v[206:209], v180
	ds_read_b128 v[216:219], v180 offset:4608
	ds_read_b128 v[236:239], v180 offset:9216
	ds_read_b128 v[240:243], v180 offset:13824
	ds_read_b128 v[244:247], v180 offset:32
	s_waitcnt lgkmcnt(4)
	v_mfma_f32_32x32x16_bf16 v[114:129], v[190:193], v[206:209], v[114:129]
	s_ashr_i32 s9, s8, 31
	s_lshl_b64 s[12:13], s[10:11], 6
	s_lshl_b64 s[4:5], s[8:9], 7
	v_mfma_f32_32x32x16_bf16 v[98:113], v[194:197], v[206:209], v[98:113]
	v_lshl_add_u64 v[138:139], v[186:187], 0, s[12:13]
	v_lshl_add_u64 v[134:135], v[138:139], 0, s[4:5]
	v_lshl_add_u64 v[138:139], v[138:139], 0, s[12:13]
	ds_read_b128 v[206:209], v180 offset:4640
	ds_read_b128 v[198:201], v181 offset:36896
	ds_read_b128 v[202:205], v181 offset:41504
	s_waitcnt lgkmcnt(6)
	v_mfma_f32_32x32x16_bf16 v[82:97], v[190:193], v[216:219], v[82:97]
	v_lshl_add_u64 v[146:147], v[138:139], 0, s[12:13]
	v_lshl_add_u64 v[142:143], v[146:147], 0, s[4:5]
	v_lshl_add_u64 v[146:147], v[146:147], 0, s[12:13]
	v_mfma_f32_32x32x16_bf16 v[66:81], v[194:197], v[216:219], v[66:81]
	v_lshl_add_u64 v[154:155], v[146:147], 0, s[12:13]
	v_lshl_add_u64 v[150:151], v[154:155], 0, s[4:5]
	v_lshl_add_u64 v[154:155], v[154:155], 0, s[12:13]
	ds_read_b128 v[216:219], v180 offset:9248
	s_waitcnt lgkmcnt(6)
	v_mfma_f32_32x32x16_bf16 v[50:65], v[190:193], v[236:239], v[50:65]
	v_lshl_add_u64 v[156:157], v[154:155], 0, s[4:5]
	v_lshl_add_u64 v[154:155], v[154:155], 0, s[12:13]
	s_lshl_b64 s[12:13], s[10:11], 6
	v_mfma_f32_32x32x16_bf16 v[34:49], v[194:197], v[236:239], v[34:49]
	v_lshl_add_u64 v[170:171], v[188:189], 0, s[12:13]
	v_lshl_add_u64 v[166:167], v[170:171], 0, s[4:5]
	v_lshl_add_u64 v[170:171], v[170:171], 0, s[12:13]
	ds_read_b128 v[236:239], v180 offset:13856
	s_waitcnt lgkmcnt(6)
	v_mfma_f32_32x32x16_bf16 v[18:33], v[190:193], v[240:243], v[18:33]
	v_lshl_add_u64 v[172:173], v[170:171], 0, s[4:5]
	v_lshl_add_u64 v[170:171], v[170:171], 0, s[12:13]
	v_lshl_add_u64 v[130:131], v[186:187], 0, s[4:5]
	v_mfma_f32_32x32x16_bf16 v[2:17], v[194:197], v[240:243], v[2:17]
	v_lshl_add_u64 v[140:141], v[138:139], 0, s[4:5]
	v_lshl_add_u64 v[148:149], v[146:147], 0, s[4:5]
	v_lshl_add_u64 v[158:159], v[154:155], 0, s[4:5]
	ds_read_b128 v[240:243], v180 offset:64
	s_waitcnt lgkmcnt(3)
	v_mfma_f32_32x32x16_bf16 v[114:129], v[198:201], v[244:247], v[114:129]
	v_lshl_add_u64 v[162:163], v[188:189], 0, s[4:5]
	v_lshl_add_u64 v[174:175], v[170:171], 0, s[4:5]
	global_load_dwordx4 v[130:133], v[130:131], off
	v_mfma_f32_32x32x16_bf16 v[98:113], v[202:205], v[244:247], v[98:113]
	s_nop 0
	global_load_dwordx4 v[134:137], v[134:135], off
	s_nop 0
	ds_read_b128 v[244:247], v180 offset:4672
	ds_read_b128 v[190:193], v181 offset:36928
	ds_read_b128 v[194:197], v181 offset:41536
	v_mfma_f32_32x32x16_bf16 v[82:97], v[198:201], v[206:209], v[82:97]
	global_load_dwordx4 v[138:141], v[140:141], off
	s_nop 0
	global_load_dwordx4 v[142:145], v[142:143], off
	v_mfma_f32_32x32x16_bf16 v[66:81], v[202:205], v[206:209], v[66:81]
	s_nop 0
	global_load_dwordx4 v[146:149], v[148:149], off
	s_nop 0
	ds_read_b128 v[206:209], v180 offset:9280
	s_waitcnt lgkmcnt(6)
	v_mfma_f32_32x32x16_bf16 v[50:65], v[198:201], v[216:219], v[50:65]
	global_load_dwordx4 v[150:153], v[150:151], off
	s_nop 0
	global_load_dwordx4 v[154:157], v[156:157], off
	v_mfma_f32_32x32x16_bf16 v[34:49], v[202:205], v[216:219], v[34:49]
	s_nop 0
	global_load_dwordx4 v[158:161], v[158:159], off
	s_nop 0
	ds_read_b128 v[216:219], v180 offset:13888
	s_waitcnt lgkmcnt(6)
	v_mfma_f32_32x32x16_bf16 v[18:33], v[198:201], v[236:239], v[18:33]
	global_load_dwordx4 v[162:165], v[162:163], off
	s_nop 0
	global_load_dwordx4 v[166:169], v[166:167], off
	v_mfma_f32_32x32x16_bf16 v[2:17], v[202:205], v[236:239], v[2:17]
	s_nop 0
	global_load_dwordx4 v[170:173], v[172:173], off
	s_nop 0
	ds_read_b128 v[236:239], v180 offset:96
	s_waitcnt lgkmcnt(3)
	v_mfma_f32_32x32x16_bf16 v[114:129], v[190:193], v[240:243], v[114:129]
	global_load_dwordx4 v[174:177], v[174:175], off
	s_add_i32 s8, s8, 1
	v_mfma_f32_32x32x16_bf16 v[98:113], v[194:197], v[240:243], v[98:113]
	ds_read_b128 v[240:243], v180 offset:4704
	ds_read_b128 v[198:201], v181 offset:36960
	ds_read_b128 v[202:205], v181 offset:41568
	v_mfma_f32_32x32x16_bf16 v[82:97], v[190:193], v[244:247], v[82:97]
	v_mfma_f32_32x32x16_bf16 v[66:81], v[194:197], v[244:247], v[66:81]
	ds_read_b128 v[244:247], v180 offset:9312
	s_waitcnt lgkmcnt(6)
	v_mfma_f32_32x32x16_bf16 v[50:65], v[190:193], v[206:209], v[50:65]
	v_mfma_f32_32x32x16_bf16 v[34:49], v[194:197], v[206:209], v[34:49]
	ds_read_b128 v[206:209], v180 offset:13920
	s_waitcnt lgkmcnt(6)
	v_mfma_f32_32x32x16_bf16 v[18:33], v[190:193], v[216:219], v[18:33]
	v_mfma_f32_32x32x16_bf16 v[2:17], v[194:197], v[216:219], v[2:17]
	s_waitcnt lgkmcnt(2)
	v_mfma_f32_32x32x16_bf16 v[114:129], v[198:201], v[236:239], v[114:129]
	v_mfma_f32_32x32x16_bf16 v[98:113], v[202:205], v[236:239], v[98:113]
	v_mfma_f32_32x32x16_bf16 v[82:97], v[198:201], v[240:243], v[82:97]
	v_mfma_f32_32x32x16_bf16 v[66:81], v[202:205], v[240:243], v[66:81]
	s_waitcnt lgkmcnt(1)
	v_mfma_f32_32x32x16_bf16 v[50:65], v[198:201], v[244:247], v[50:65]
	v_mfma_f32_32x32x16_bf16 v[34:49], v[202:205], v[244:247], v[34:49]
	s_waitcnt lgkmcnt(0)
	v_mfma_f32_32x32x16_bf16 v[18:33], v[198:201], v[206:209], v[18:33]
	v_mfma_f32_32x32x16_bf16 v[2:17], v[202:205], v[206:209], v[2:17]
	s_cmp_lg_u32 s8, s19
	s_setprio 0
	s_cbranch_scc1 .Ltail_92
	s_add_i32 s21, s14, 1
	s_cmp_ge_i32 s21, s16
	s_cbranch_scc1 .Lx91_92
	s_bfe_u32 s22, s21, 0x20001
	s_bitcmp1_b32 s14, 0
	s_cselect_b64 s[4:5], -1, 0
	s_and_b64 vcc, exec, s[4:5]
	s_cbranch_vccnz .Lx89_92
	s_cmp_lt_i32 s22, 1
	s_mov_b64 s[4:5], 0xfc00000
	s_cbranch_scc1 .Lx88_92
	s_cmp_eq_u32 s22, 1
	s_mov_b64 s[8:9], -1
	s_cbranch_scc1 .Lx86_92
	s_cmp_eq_u32 s22, 2
	s_mov_b32 s4, 0x4c00000
	s_cselect_b32 s80, s4, 0x9c00000
	s_mov_b64 s[8:9], 0
	s_mov_b64 s[4:5], s[80:81]

.Lx91_92:
	s_mov_b32 s8, 0
	s_mov_b32 s14, s21
	s_branch .Ltail_92
.LBB0_92:
	s_waitcnt lgkmcnt(0)
	s_barrier
	s_setprio 2
	ds_read_b128 v[190:193], v181 offset:36864
	ds_read_b128 v[194:197], v181 offset:41472
	ds_read_b128 v[206:209], v180
	ds_read_b128 v[216:219], v180 offset:4608
	ds_read_b128 v[236:239], v180 offset:9216
	ds_read_b128 v[240:243], v180 offset:13824
	ds_read_b128 v[244:247], v180 offset:32
	s_waitcnt lgkmcnt(4)
	v_mfma_f32_32x32x16_bf16 v[114:129], v[190:193], v[206:209], v[114:129]
	v_mfma_f32_32x32x16_bf16 v[98:113], v[194:197], v[206:209], v[98:113]
	ds_read_b128 v[206:209], v180 offset:4640
	ds_read_b128 v[198:201], v181 offset:36896
	ds_read_b128 v[202:205], v181 offset:41504
	s_waitcnt lgkmcnt(6)
	v_mfma_f32_32x32x16_bf16 v[82:97], v[190:193], v[216:219], v[82:97]
	v_mfma_f32_32x32x16_bf16 v[66:81], v[194:197], v[216:219], v[66:81]
	ds_read_b128 v[216:219], v180 offset:9248
	s_waitcnt lgkmcnt(6)
	v_mfma_f32_32x32x16_bf16 v[50:65], v[190:193], v[236:239], v[50:65]
	v_mfma_f32_32x32x16_bf16 v[34:49], v[194:197], v[236:239], v[34:49]
	ds_read_b128 v[236:239], v180 offset:13856
	s_waitcnt lgkmcnt(6)
	v_mfma_f32_32x32x16_bf16 v[18:33], v[190:193], v[240:243], v[18:33]
	v_mfma_f32_32x32x16_bf16 v[2:17], v[194:197], v[240:243], v[2:17]
	ds_read_b128 v[240:243], v180 offset:64
	s_waitcnt lgkmcnt(3)
	v_mfma_f32_32x32x16_bf16 v[114:129], v[198:201], v[244:247], v[114:129]
	v_mfma_f32_32x32x16_bf16 v[98:113], v[202:205], v[244:247], v[98:113]
	ds_read_b128 v[244:247], v180 offset:4672
	ds_read_b128 v[190:193], v181 offset:36928
	ds_read_b128 v[194:197], v181 offset:41536
	v_mfma_f32_32x32x16_bf16 v[82:97], v[198:201], v[206:209], v[82:97]
	v_mfma_f32_32x32x16_bf16 v[66:81], v[202:205], v[206:209], v[66:81]
	ds_read_b128 v[206:209], v180 offset:9280
	s_waitcnt lgkmcnt(6)
	v_mfma_f32_32x32x16_bf16 v[50:65], v[198:201], v[216:219], v[50:65]
	v_mfma_f32_32x32x16_bf16 v[34:49], v[202:205], v[216:219], v[34:49]
	ds_read_b128 v[216:219], v180 offset:13888
	s_waitcnt lgkmcnt(6)
	v_mfma_f32_32x32x16_bf16 v[18:33], v[198:201], v[236:239], v[18:33]
	v_mfma_f32_32x32x16_bf16 v[2:17], v[202:205], v[236:239], v[2:17]
	ds_read_b128 v[236:239], v180 offset:96
	s_waitcnt lgkmcnt(3)
	v_mfma_f32_32x32x16_bf16 v[114:129], v[190:193], v[240:243], v[114:129]
	v_mfma_f32_32x32x16_bf16 v[98:113], v[194:197], v[240:243], v[98:113]
	ds_read_b128 v[240:243], v180 offset:4704
	ds_read_b128 v[198:201], v181 offset:36960
	ds_read_b128 v[202:205], v181 offset:41568
	v_mfma_f32_32x32x16_bf16 v[82:97], v[190:193], v[244:247], v[82:97]
	v_mfma_f32_32x32x16_bf16 v[66:81], v[194:197], v[244:247], v[66:81]
	ds_read_b128 v[244:247], v180 offset:9312
	s_waitcnt lgkmcnt(6)
	v_mfma_f32_32x32x16_bf16 v[50:65], v[190:193], v[206:209], v[50:65]
	v_mfma_f32_32x32x16_bf16 v[34:49], v[194:197], v[206:209], v[34:49]
	ds_read_b128 v[206:209], v180 offset:13920
	s_waitcnt lgkmcnt(6)
	v_mfma_f32_32x32x16_bf16 v[18:33], v[190:193], v[216:219], v[18:33]
	v_mfma_f32_32x32x16_bf16 v[2:17], v[194:197], v[216:219], v[2:17]
	s_waitcnt lgkmcnt(2)
	v_mfma_f32_32x32x16_bf16 v[114:129], v[198:201], v[236:239], v[114:129]
	v_mfma_f32_32x32x16_bf16 v[98:113], v[202:205], v[236:239], v[98:113]
	v_mfma_f32_32x32x16_bf16 v[82:97], v[198:201], v[240:243], v[82:97]
	v_mfma_f32_32x32x16_bf16 v[66:81], v[202:205], v[240:243], v[66:81]
	s_waitcnt lgkmcnt(1)
	v_mfma_f32_32x32x16_bf16 v[50:65], v[198:201], v[244:247], v[50:65]
	v_mfma_f32_32x32x16_bf16 v[34:49], v[202:205], v[244:247], v[34:49]
	s_waitcnt lgkmcnt(0)
	v_mfma_f32_32x32x16_bf16 v[18:33], v[198:201], v[206:209], v[18:33]
	v_mfma_f32_32x32x16_bf16 v[2:17], v[202:205], v[206:209], v[2:17]
	s_setprio 0
.Ltail_92:
	s_add_i32 s20, s20, 1
	s_cmp_lg_u32 s20, s17
	s_cbranch_scc1 .LBB0_78
	v_mov_b32_e32 v192, v222
	s_bitcmp1_b32 s18, 0
	s_cselect_b64 s[12:13], -1, 0
	v_ashrrev_i32_e32 v193, 31, v192
	v_lshl_add_u64 v[190:191], v[192:193], 2, s[6:7]
	s_mov_b64 s[4:5], -1
	s_and_b64 vcc, exec, s[12:13]
	s_cbranch_vccz .LBB0_159
	s_ashr_i32 s4, s18, 3
	s_mul_i32 s4, s4, s82
	s_add_i32 s4, s4, s63
	s_ashr_i32 s5, s4, 31
	s_lshr_b32 s5, s5, 28
	s_add_i32 s5, s4, s5
	s_ashr_i32 s12, s5, 4
	s_and_b32 s5, s5, -16
	s_sub_i32 s13, s4, s5
	s_lshl_b32 s4, s12, 1
	s_and_b32 s5, s13, 1
	s_or_b32 s12, s5, s4
	v_readlane_b32 s4, v252, 35
	s_and_b32 s9, s18, 7
	s_sub_i32 s15, 0x7f, s12
	v_readlane_b32 s5, v252, 36
	s_and_b64 s[4:5], s[4:5], exec
	s_cselect_b32 s4, s15, s12
	s_ashr_i32 s5, s4, 31
	v_and_b32_e32 v194, 0xffffff80, v192
	s_lshl_b64 s[4:5], s[4:5], 8
	v_ashrrev_i32_e32 v195, 31, v194
	v_lshl_add_u64 v[194:195], s[4:5], 0, v[194:195]
	v_lshrrev_b32_e32 v179, 3, v192
	v_and_or_b32 v194, v192, 31, v194
	v_and_b32_e32 v179, 4, v179
	v_and_b32_e32 v0, 64, v192
	v_lshlrev_b64 v[192:193], 11, v[194:195]
	v_lshlrev_b32_e32 v194, 1, v179
	global_load_dword v179, v[190:191], off
	global_load_dword v183, v[190:191], off offset:1024
	s_lshl_b32 s4, s13, 6
	s_and_b32 s4, s4, 0xffffff80
	s_ashr_i32 s5, s4, 31
	v_lshl_add_u64 v[192:193], s[2:3], 0, v[192:193]
	v_lshl_add_u64 v[192:193], s[4:5], 1, v[192:193]
	v_lshlrev_b32_e32 v0, 1, v0
	s_cmp_lg_u32 s9, 1
	v_lshl_add_u64 v[196:197], v[192:193], 0, v[0:1]
	v_mov_b32_e32 v195, v1
	s_cselect_b64 s[12:13], -1, 0
	s_cmp_eq_u32 s9, 1
	v_lshl_add_u64 v[196:197], v[196:197], 0, v[194:195]
	s_waitcnt vmcnt(1)
	v_lshlrev_b32_e32 v198, 16, v179
	v_and_b32_e32 v199, 0xffff0000, v179
	s_waitcnt vmcnt(0)
	v_lshlrev_b32_e32 v200, 16, v183
	v_and_b32_e32 v201, 0xffff0000, v183
	v_pk_mul_f32 v[198:199], v[114:115], v[198:199]
	v_pk_mul_f32 v[200:201], v[116:117], v[200:201]
	s_cbranch_scc1 .LBB0_96
	global_load_dwordx2 v[202:203], v[196:197], off
	s_waitcnt vmcnt(0)
	v_lshlrev_b32_e32 v204, 16, v202
	v_and_b32_e32 v205, 0xffff0000, v202
	v_lshlrev_b32_e32 v202, 16, v203
	v_and_b32_e32 v203, 0xffff0000, v203
	v_pk_add_f32 v[198:199], v[198:199], v[204:205]
	v_pk_add_f32 v[200:201], v[200:201], v[202:203]

.LcL_647:
	s_waitcnt lgkmcnt(0)
	s_barrier
	s_setprio 2
	ds_read_b128 v[178:181], v183 offset:36864
	ds_read_b128 v[194:197], v183 offset:41472
	ds_read_b128 v[206:209], v182
	ds_read_b128 v[216:219], v182 offset:4608
	ds_read_b128 v[236:239], v182 offset:9216
	ds_read_b128 v[240:243], v182 offset:13824
	ds_read_b128 v[244:247], v182 offset:32
	s_waitcnt lgkmcnt(4)
	v_mfma_f32_32x32x16_bf16 v[114:129], v[178:181], v[206:209], v[114:129]
	s_ashr_i32 s1, s0, 31
	s_lshl_b64 s[4:5], s[0:1], 7
	v_lshl_add_u64 v[154:155], v[184:185], 0, s[4:5]
	v_mfma_f32_32x32x16_bf16 v[50:65], v[194:197], v[206:209], v[50:65]
	v_add_co_u32_e32 v130, vcc, 0x10000, v154
	v_lshl_add_u64 v[170:171], v[186:187], 0, s[4:5]
	s_nop 0
	ds_read_b128 v[206:209], v182 offset:4640
	ds_read_b128 v[198:201], v183 offset:36896
	ds_read_b128 v[202:205], v183 offset:41504
	s_waitcnt lgkmcnt(6)
	v_mfma_f32_32x32x16_bf16 v[98:113], v[178:181], v[216:219], v[98:113]
	v_addc_co_u32_e32 v131, vcc, 0, v155, vcc
	v_add_co_u32_e32 v134, vcc, 0x20000, v154
	global_load_dwordx4 v[142:145], v[154:155], off
	v_mfma_f32_32x32x16_bf16 v[34:49], v[194:197], v[216:219], v[34:49]
	s_nop 0
	global_load_dwordx4 v[130:133], v[130:131], off
	v_addc_co_u32_e32 v135, vcc, 0, v155, vcc
	ds_read_b128 v[216:219], v182 offset:9248
	s_waitcnt lgkmcnt(6)
	v_mfma_f32_32x32x16_bf16 v[82:97], v[178:181], v[236:239], v[82:97]
	v_add_co_u32_e32 v138, vcc, 0x30000, v154
	s_add_i32 s0, s0, 1
	s_nop 0
	v_mfma_f32_32x32x16_bf16 v[18:33], v[194:197], v[236:239], v[18:33]
	v_addc_co_u32_e32 v139, vcc, 0, v155, vcc
	v_add_co_u32_e32 v146, vcc, 0x40000, v154
	global_load_dwordx4 v[134:137], v[134:135], off
	ds_read_b128 v[236:239], v182 offset:13856
	s_waitcnt lgkmcnt(6)
	v_mfma_f32_32x32x16_bf16 v[66:81], v[178:181], v[240:243], v[66:81]
	s_nop 0
	global_load_dwordx4 v[138:141], v[138:139], off
	v_addc_co_u32_e32 v147, vcc, 0, v155, vcc
	v_mfma_f32_32x32x16_bf16 v[2:17], v[194:197], v[240:243], v[2:17]
	v_add_co_u32_e32 v150, vcc, 0x50000, v154
	s_nop 0
	v_addc_co_u32_e32 v151, vcc, 0, v155, vcc
	ds_read_b128 v[240:243], v182 offset:64
	s_waitcnt lgkmcnt(3)
	v_mfma_f32_32x32x16_bf16 v[114:129], v[198:201], v[244:247], v[114:129]
	v_add_co_u32_e32 v156, vcc, 0x60000, v154
	global_load_dwordx4 v[146:149], v[146:147], off
	s_nop 0
	v_mfma_f32_32x32x16_bf16 v[50:65], v[202:205], v[244:247], v[50:65]
	global_load_dwordx4 v[150:153], v[150:151], off
	v_addc_co_u32_e32 v157, vcc, 0, v155, vcc
	v_add_co_u32_e32 v158, vcc, 0x70000, v154
	ds_read_b128 v[244:247], v182 offset:4672
	ds_read_b128 v[178:181], v183 offset:36928
	ds_read_b128 v[194:197], v183 offset:41536
	v_mfma_f32_32x32x16_bf16 v[98:113], v[198:201], v[206:209], v[98:113]
	s_nop 1
	v_addc_co_u32_e32 v159, vcc, 0, v155, vcc
	v_add_co_u32_e32 v166, vcc, 0x10000, v170
	v_mfma_f32_32x32x16_bf16 v[34:49], v[202:205], v[206:209], v[34:49]
	global_load_dwordx4 v[154:157], v[156:157], off
	s_nop 0
	global_load_dwordx4 v[158:161], v[158:159], off
	ds_read_b128 v[206:209], v182 offset:9280
	s_waitcnt lgkmcnt(6)
	v_mfma_f32_32x32x16_bf16 v[82:97], v[198:201], v[216:219], v[82:97]
	v_addc_co_u32_e32 v167, vcc, 0, v171, vcc
	v_add_co_u32_e32 v172, vcc, 0x20000, v170
	global_load_dwordx4 v[162:165], v[170:171], off
	v_mfma_f32_32x32x16_bf16 v[18:33], v[202:205], v[216:219], v[18:33]
	s_nop 0
	global_load_dwordx4 v[166:169], v[166:167], off
	v_addc_co_u32_e32 v173, vcc, 0, v171, vcc
	ds_read_b128 v[216:219], v182 offset:13888
	s_waitcnt lgkmcnt(6)
	v_mfma_f32_32x32x16_bf16 v[66:81], v[198:201], v[236:239], v[66:81]
	v_add_co_u32_e32 v174, vcc, 0x30000, v170
	s_nop 1
	v_addc_co_u32_e32 v175, vcc, 0, v171, vcc
	v_mfma_f32_32x32x16_bf16 v[2:17], v[202:205], v[236:239], v[2:17]
	global_load_dwordx4 v[170:173], v[172:173], off
	s_nop 0
	global_load_dwordx4 v[174:177], v[174:175], off
	ds_read_b128 v[236:239], v182 offset:96
	s_waitcnt lgkmcnt(3)
	v_mfma_f32_32x32x16_bf16 v[114:129], v[178:181], v[240:243], v[114:129]
	v_mfma_f32_32x32x16_bf16 v[50:65], v[194:197], v[240:243], v[50:65]
	ds_read_b128 v[240:243], v182 offset:4704
	ds_read_b128 v[198:201], v183 offset:36960
	ds_read_b128 v[202:205], v183 offset:41568
	v_mfma_f32_32x32x16_bf16 v[98:113], v[178:181], v[244:247], v[98:113]
	v_mfma_f32_32x32x16_bf16 v[34:49], v[194:197], v[244:247], v[34:49]
	ds_read_b128 v[244:247], v182 offset:9312
	s_waitcnt lgkmcnt(6)
	v_mfma_f32_32x32x16_bf16 v[82:97], v[178:181], v[206:209], v[82:97]
	v_mfma_f32_32x32x16_bf16 v[18:33], v[194:197], v[206:209], v[18:33]
	ds_read_b128 v[206:209], v182 offset:13920
	s_waitcnt lgkmcnt(6)
	v_mfma_f32_32x32x16_bf16 v[66:81], v[178:181], v[216:219], v[66:81]
	v_mfma_f32_32x32x16_bf16 v[2:17], v[194:197], v[216:219], v[2:17]
	s_waitcnt lgkmcnt(2)
	v_mfma_f32_32x32x16_bf16 v[114:129], v[198:201], v[236:239], v[114:129]
	v_mfma_f32_32x32x16_bf16 v[50:65], v[202:205], v[236:239], v[50:65]
	v_mfma_f32_32x32x16_bf16 v[98:113], v[198:201], v[240:243], v[98:113]
	v_mfma_f32_32x32x16_bf16 v[34:49], v[202:205], v[240:243], v[34:49]
	s_waitcnt lgkmcnt(1)
	v_mfma_f32_32x32x16_bf16 v[82:97], v[198:201], v[244:247], v[82:97]
	v_mfma_f32_32x32x16_bf16 v[18:33], v[202:205], v[244:247], v[18:33]
	s_waitcnt lgkmcnt(0)
	v_mfma_f32_32x32x16_bf16 v[66:81], v[198:201], v[206:209], v[66:81]
	v_mfma_f32_32x32x16_bf16 v[2:17], v[202:205], v[206:209], v[2:17]
	s_cmp_lg_u32 s0, 16
	s_setprio 0
	s_cbranch_scc1 .Ltail_647
	s_add_i32 s10, s10, 1
	s_cmp_ge_i32 s10, s8
	s_cbranch_scc1 .Lx646_647
	s_mul_i32 s0, s10, s82
	s_add_i32 s0, s0, s63
	s_ashr_i32 s1, s0, 31
	s_lshr_b32 s1, s1, 26
	s_add_i32 s1, s0, s1
	s_ashr_i32 s3, s1, 6
	s_andn2_b32 s1, s1, 63
	s_sub_i32 s0, s0, s1
	s_lshl_b32 s1, s3, 1
	s_and_b32 s3, s0, 1
	s_or_b32 s1, s3, s1
	v_readlane_b32 s4, v252, 35
	s_ashr_i32 s0, s0, 1
	s_sub_i32 s3, 0x7f, s1
	v_readlane_b32 s5, v252, 36
	s_and_b64 s[4:5], s[4:5], exec
	s_cselect_b32 s4, s3, s1
	s_ashr_i32 s5, s4, 31
	s_ashr_i32 s1, s0, 31
	s_lshl_b64 s[4:5], s[4:5], 19
	s_lshl_b64 s[0:1], s[0:1], 18
	v_lshl_add_u64 v[184:185], v[190:191], 0, s[4:5]
	v_lshl_add_u64 v[186:187], v[192:193], 0, s[0:1]

.LBB0_647:
	s_waitcnt lgkmcnt(0)
	s_barrier
	s_setprio 2
	ds_read_b128 v[178:181], v183 offset:36864
	ds_read_b128 v[194:197], v183 offset:41472
	ds_read_b128 v[206:209], v182
	ds_read_b128 v[216:219], v182 offset:4608
	ds_read_b128 v[236:239], v182 offset:9216
	ds_read_b128 v[240:243], v182 offset:13824
	ds_read_b128 v[244:247], v182 offset:32
	s_waitcnt lgkmcnt(4)
	v_mfma_f32_32x32x16_bf16 v[114:129], v[178:181], v[206:209], v[114:129]
	v_mfma_f32_32x32x16_bf16 v[50:65], v[194:197], v[206:209], v[50:65]
	ds_read_b128 v[206:209], v182 offset:4640
	ds_read_b128 v[198:201], v183 offset:36896
	ds_read_b128 v[202:205], v183 offset:41504
	s_waitcnt lgkmcnt(6)
	v_mfma_f32_32x32x16_bf16 v[98:113], v[178:181], v[216:219], v[98:113]
	v_mfma_f32_32x32x16_bf16 v[34:49], v[194:197], v[216:219], v[34:49]
	ds_read_b128 v[216:219], v182 offset:9248
	s_waitcnt lgkmcnt(6)
	v_mfma_f32_32x32x16_bf16 v[82:97], v[178:181], v[236:239], v[82:97]
	v_mfma_f32_32x32x16_bf16 v[18:33], v[194:197], v[236:239], v[18:33]
	ds_read_b128 v[236:239], v182 offset:13856
	s_waitcnt lgkmcnt(6)
	v_mfma_f32_32x32x16_bf16 v[66:81], v[178:181], v[240:243], v[66:81]
	v_mfma_f32_32x32x16_bf16 v[2:17], v[194:197], v[240:243], v[2:17]
	ds_read_b128 v[240:243], v182 offset:64
	s_waitcnt lgkmcnt(3)
	v_mfma_f32_32x32x16_bf16 v[114:129], v[198:201], v[244:247], v[114:129]
	v_mfma_f32_32x32x16_bf16 v[50:65], v[202:205], v[244:247], v[50:65]
	ds_read_b128 v[244:247], v182 offset:4672
	ds_read_b128 v[178:181], v183 offset:36928
	ds_read_b128 v[194:197], v183 offset:41536
	v_mfma_f32_32x32x16_bf16 v[98:113], v[198:201], v[206:209], v[98:113]
	v_mfma_f32_32x32x16_bf16 v[34:49], v[202:205], v[206:209], v[34:49]
	ds_read_b128 v[206:209], v182 offset:9280
	s_waitcnt lgkmcnt(6)
	v_mfma_f32_32x32x16_bf16 v[82:97], v[198:201], v[216:219], v[82:97]
	v_mfma_f32_32x32x16_bf16 v[18:33], v[202:205], v[216:219], v[18:33]
	ds_read_b128 v[216:219], v182 offset:13888
	s_waitcnt lgkmcnt(6)
	v_mfma_f32_32x32x16_bf16 v[66:81], v[198:201], v[236:239], v[66:81]
	v_mfma_f32_32x32x16_bf16 v[2:17], v[202:205], v[236:239], v[2:17]
	ds_read_b128 v[236:239], v182 offset:96
	s_waitcnt lgkmcnt(3)
	v_mfma_f32_32x32x16_bf16 v[114:129], v[178:181], v[240:243], v[114:129]
	v_mfma_f32_32x32x16_bf16 v[50:65], v[194:197], v[240:243], v[50:65]
	ds_read_b128 v[240:243], v182 offset:4704
	ds_read_b128 v[198:201], v183 offset:36960
	ds_read_b128 v[202:205], v183 offset:41568
	v_mfma_f32_32x32x16_bf16 v[98:113], v[178:181], v[244:247], v[98:113]
	v_mfma_f32_32x32x16_bf16 v[34:49], v[194:197], v[244:247], v[34:49]
	ds_read_b128 v[244:247], v182 offset:9312
	s_waitcnt lgkmcnt(6)
	v_mfma_f32_32x32x16_bf16 v[82:97], v[178:181], v[206:209], v[82:97]
	v_mfma_f32_32x32x16_bf16 v[18:33], v[194:197], v[206:209], v[18:33]
	ds_read_b128 v[206:209], v182 offset:13920
	s_waitcnt lgkmcnt(6)
	v_mfma_f32_32x32x16_bf16 v[66:81], v[178:181], v[216:219], v[66:81]
	v_mfma_f32_32x32x16_bf16 v[2:17], v[194:197], v[216:219], v[2:17]
	s_waitcnt lgkmcnt(2)
	v_mfma_f32_32x32x16_bf16 v[114:129], v[198:201], v[236:239], v[114:129]
	v_mfma_f32_32x32x16_bf16 v[50:65], v[202:205], v[236:239], v[50:65]
	v_mfma_f32_32x32x16_bf16 v[98:113], v[198:201], v[240:243], v[98:113]
	v_mfma_f32_32x32x16_bf16 v[34:49], v[202:205], v[240:243], v[34:49]
	s_waitcnt lgkmcnt(1)
	v_mfma_f32_32x32x16_bf16 v[82:97], v[198:201], v[244:247], v[82:97]
	v_mfma_f32_32x32x16_bf16 v[18:33], v[202:205], v[244:247], v[18:33]
	s_waitcnt lgkmcnt(0)
	v_mfma_f32_32x32x16_bf16 v[66:81], v[198:201], v[206:209], v[66:81]
	v_mfma_f32_32x32x16_bf16 v[2:17], v[202:205], v[206:209], v[2:17]
	s_setprio 0
.Ltail_647:
	s_add_i32 s2, s2, 1
	s_cmp_lg_u32 s2, 16
	s_cbranch_scc1 .LBB0_641
	s_mul_i32 s1, s9, s82
	s_add_i32 s1, s1, s63
	s_ashr_i32 s2, s1, 31
	s_lshr_b32 s2, s2, 26
	s_add_i32 s2, s1, s2
	s_ashr_i32 s3, s2, 6
	s_andn2_b32 s2, s2, 63
	s_sub_i32 s1, s1, s2
	s_lshl_b32 s2, s3, 1
	s_and_b32 s3, s1, 1
	s_or_b32 s4, s3, s2
	v_readlane_b32 s2, v252, 35
	s_sub_i32 s5, 0x7f, s4
	v_readlane_b32 s3, v252, 36
	s_and_b64 s[2:3], s[2:3], exec
	v_mov_b32_e32 v0, v222
	s_cselect_b32 s2, s5, s4
	s_lshl_b32 s1, s1, 1
	s_and_b32 s1, s1, -4
	v_lshrrev_b32_e32 v178, 5, v0
	v_and_or_b32 v220, v178, 2, s1
	v_readlane_b32 s1, v250, 18
	s_getpc_b64 s[4:5]
	s_add_u32 s4, s4, c_segs@rel32@lo+16
	s_addc_u32 s5, s5, c_segs@rel32@hi+24
	v_cmp_le_i32_e32 vcc, s1, v220
	v_readlane_b32 s1, v250, 19
	v_and_b32_e32 v189, 31, v0
	v_cndmask_b32_e64 v178, 0, 1, vcc
	v_cmp_gt_i32_e32 vcc, s1, v220
	v_readlane_b32 s1, v250, 20
	v_mov_b32_e32 v203, v1
	v_cndmask_b32_e32 v178, 2, v178, vcc
	v_cmp_gt_i32_e32 vcc, s1, v220
	v_readlane_b32 s1, v250, 21
	v_mov_b32_e32 v201, v1
	v_cndmask_b32_e32 v178, 3, v178, vcc
	v_cmp_gt_i32_e32 vcc, s1, v220
	v_readlane_b32 s1, v250, 22
	v_mov_b32_e32 v199, v1
	v_cndmask_b32_e32 v178, 4, v178, vcc
	v_cmp_gt_i32_e32 vcc, s1, v220
	v_readlane_b32 s1, v250, 23
	v_mov_b32_e32 v197, v1
	v_cndmask_b32_e32 v178, 5, v178, vcc
	v_cmp_gt_i32_e32 vcc, s1, v220
	v_readlane_b32 s1, v250, 24
	s_nop 0
	v_cndmask_b32_e32 v178, 6, v178, vcc
	v_cmp_gt_i32_e32 vcc, s1, v220
	v_readlane_b32 s1, v250, 25
	s_nop 0
	v_cndmask_b32_e32 v178, 7, v178, vcc
	v_cmp_gt_i32_e32 vcc, s1, v220
	v_readlane_b32 s1, v250, 26
	s_nop 0
	v_cndmask_b32_e32 v178, 8, v178, vcc
	v_cmp_gt_i32_e32 vcc, s1, v220
	v_readlane_b32 s1, v250, 27
	s_nop 0
	v_cndmask_b32_e32 v178, 9, v178, vcc
	v_cmp_gt_i32_e32 vcc, s1, v220
	v_readlane_b32 s1, v250, 28
	s_nop 0
	v_cndmask_b32_e32 v178, 10, v178, vcc
	v_cmp_gt_i32_e32 vcc, s1, v220
	v_readlane_b32 s1, v250, 29
	s_nop 0
	v_cndmask_b32_e32 v178, 11, v178, vcc
	v_cmp_gt_i32_e32 vcc, s1, v220
	v_readlane_b32 s1, v250, 30
	s_nop 0
	v_cndmask_b32_e32 v178, 12, v178, vcc
	v_cmp_gt_i32_e32 vcc, s1, v220
	v_readlane_b32 s1, v250, 31
	s_nop 0
	v_cndmask_b32_e32 v178, 13, v178, vcc
	v_cmp_gt_i32_e32 vcc, s1, v220
	v_readlane_b32 s1, v250, 32
	s_nop 0
	v_cndmask_b32_e32 v178, 14, v178, vcc
	v_cmp_gt_i32_e32 vcc, s1, v220
	v_readlane_b32 s1, v250, 33
	s_nop 0
	v_cndmask_b32_e32 v178, 15, v178, vcc
	v_cmp_gt_i32_e32 vcc, s1, v220
	v_readlane_b32 s1, v250, 34
	s_nop 0
	v_cndmask_b32_e32 v178, 16, v178, vcc
	v_cmp_gt_i32_e32 vcc, s1, v220
	s_nop 1
	v_cndmask_b32_e32 v181, 17, v178, vcc
	v_mad_u64_u32 v[178:179], s[4:5], v181, 24, s[4:5]
	s_getpc_b64 s[4:5]
	s_add_u32 s4, s4, c_segs@rel32@lo+4
	s_addc_u32 s5, s5, c_segs@rel32@hi+12
	v_mad_u64_u32 v[194:195], s[4:5], v181, 24, s[4:5]
	global_load_dwordx3 v[178:180], v[178:179], off
	v_lshrrev_b32_e32 v181, 3, v0
	global_load_dword v206, v[194:195], off
	v_and_b32_e32 v194, 0xffffff80, v0
	v_bfe_u32 v0, v0, 3, 3
	v_and_b32_e32 v219, 4, v181
	v_or_b32_e32 v181, 3, v0
	v_or_b32_e32 v196, 11, v0
	v_lshlrev_b32_e32 v204, 14, v0
	v_cvt_f32_ubyte0_e32 v205, v219
	v_or_b32_e32 v207, 1, v219
	v_or_b32_e32 v208, 2, v219
	v_cvt_f32_ubyte0_e32 v181, v181
	v_or_b32_e32 v209, 8, v219
	v_or_b32_e32 v211, 9, v219
	v_or_b32_e32 v213, 10, v219
	v_cvt_f32_ubyte0_e32 v215, v196
	v_and_b32_e32 v0, 0x10000, v204
	v_or_b32_e32 v202, 0xc000, v204
	v_or_b32_e32 v200, 0x2c000, v204
	v_or_b32_e32 v198, 0x4c000, v204
	v_or_b32_e32 v196, 0x6c000, v204
	v_mul_f32_e32 v204, 0xbf549a78, v205
	v_cvt_f32_ubyte0_e32 v205, v207
	v_cvt_f32_ubyte0_e32 v207, v208
	v_mul_f32_e32 v181, 0xbf549a78, v181
	v_cvt_f32_ubyte0_e32 v208, v209
	v_cvt_f32_ubyte0_e32 v209, v211
	v_cvt_f32_ubyte0_e32 v211, v213
	v_mul_f32_e32 v213, 0xbf549a78, v215
	v_exp_f32_e32 v217, v204
	v_mul_f32_e32 v204, 0xbf549a78, v205
	v_mul_f32_e32 v205, 0xbf549a78, v207
	v_exp_f32_e32 v215, v181
	v_mul_f32_e32 v181, 0xbf549a78, v208
	v_mul_f32_e32 v207, 0xbf549a78, v209
	v_mul_f32_e32 v209, 0xbf549a78, v211
	s_ashr_i32 s3, s2, 31
	v_ashrrev_i32_e32 v195, 31, v194
	v_exp_f32_e32 v208, v213
	v_exp_f32_e32 v218, v204
	v_exp_f32_e32 v216, v205
	v_exp_f32_e32 v213, v181
	v_exp_f32_e32 v211, v207
	v_exp_f32_e32 v209, v209
	s_lshl_b64 s[2:3], s[2:3], 8
	v_lshl_add_u64 v[194:195], s[2:3], 0, v[194:195]
	v_mov_b32_e32 v181, v1
	v_readlane_b32 s2, v252, 45
	v_readlane_b32 s3, v252, 46
	v_and_b32_e32 v221, 0x1f80, v194
	v_lshrrev_b64 v[204:205], 13, v[194:195]
	s_waitcnt vmcnt(1)
	v_lshlrev_b64 v[180:181], 10, v[180:181]
	v_lshl_add_u64 v[180:181], s[2:3], 0, v[180:181]
	s_waitcnt vmcnt(0)
	v_sub_u32_e32 v206, v220, v206
	v_lshlrev_b32_e32 v206, 5, v206
	v_cmp_lt_i32_e32 vcc, 0, v179
	s_and_saveexec_b64 s[2:3], vcc
	s_xor_b64 s[2:3], exec, s[2:3]
	s_cbranch_execz .LBB0_656
	v_cmp_lt_i32_e32 vcc, 1, v179
	s_and_saveexec_b64 s[4:5], vcc
	s_xor_b64 s[4:5], exec, s[4:5]
	s_cbranch_execz .LBB0_653
	v_cmp_eq_u32_e32 vcc, 2, v179
	s_and_saveexec_b64 s[6:7], vcc
	s_cbranch_execz .LBB0_652
	v_ashrrev_i32_e32 v207, 31, v206
	v_lshl_add_u64 v[180:181], v[206:207], 1, v[180:181]
	v_lshlrev_b32_e32 v206, 1, v219
	v_mov_b32_e32 v207, v1
	s_movk_i32 s1, 0x1f80
	v_lshl_add_u64 v[180:181], v[180:181], 0, v[206:207]
	v_and_or_b32 v206, v194, s1, v189
	v_cvt_f32_u32_e32 v226, v206
	s_mov_b32 s14, 0x6dc9c883
	s_mov_b32 s15, 0x3fc45f30
	v_ashrrev_i32_e32 v179, 31, v178
	v_mul_f32_e32 v206, v217, v226
	v_cvt_f64_f32_e32 v[206:207], v206
	v_mul_f64 v[236:237], v[206:207], s[14:15]
	v_floor_f64_e32 v[236:237], v[236:237]
	v_fma_f64 v[206:207], v[206:207], s[14:15], -v[236:237]
	v_cvt_f32_f64_e32 v207, v[206:207]
	v_sin_f32_e32 v206, v207
	v_cos_f32_e32 v236, v207
	v_mul_f32_e32 v207, v218, v226
	v_cvt_f64_f32_e32 v[238:239], v207
	v_mul_f64 v[240:241], v[238:239], s[14:15]
	v_floor_f64_e32 v[240:241], v[240:241]
	v_fma_f64 v[238:239], v[238:239], s[14:15], -v[240:241]
	v_cvt_f32_f64_e32 v237, v[238:239]
	v_sin_f32_e32 v207, v237
	v_cos_f32_e32 v237, v237
	s_movk_i32 s1, 0x1fa0
	v_pk_mul_f32 v[238:239], v[122:123], v[206:207]
	v_pk_mul_f32 v[122:123], v[122:123], v[236:237]
	v_pk_fma_f32 v[238:239], v[114:115], v[236:237], v[238:239] neg_lo:[0,0,1] neg_hi:[0,0,1]
	v_pk_fma_f32 v[122:123], v[114:115], v[206:207], v[122:123]
	v_mul_f32_e32 v114, v216, v226
	v_cvt_f64_f32_e32 v[114:115], v114
	v_mul_f64 v[206:207], v[114:115], s[14:15]
	v_floor_f64_e32 v[206:207], v[206:207]
	v_fma_f64 v[114:115], v[114:115], s[14:15], -v[206:207]
	v_cvt_f32_f64_e32 v115, v[114:115]
	v_sin_f32_e32 v114, v115
	v_cos_f32_e32 v206, v115
	v_mul_f32_e32 v115, v215, v226
	v_cvt_f64_f32_e32 v[236:237], v115
	v_mul_f64 v[240:241], v[236:237], s[14:15]
	v_floor_f64_e32 v[240:241], v[240:241]
	v_fma_f64 v[236:237], v[236:237], s[14:15], -v[240:241]
	v_cvt_f32_f64_e32 v207, v[236:237]
	v_sin_f32_e32 v115, v207
	v_cos_f32_e32 v207, v207
	v_cvt_pk_bf16_f32 v122, v122, v123
	v_pk_mul_f32 v[236:237], v[124:125], v[114:115]
	v_pk_mul_f32 v[124:125], v[124:125], v[206:207]
	v_pk_fma_f32 v[236:237], v[116:117], v[206:207], v[236:237] neg_lo:[0,0,1] neg_hi:[0,0,1]
	v_pk_fma_f32 v[116:117], v[116:117], v[114:115], v[124:125]
	v_mul_f32_e32 v114, v213, v226
	v_cvt_f64_f32_e32 v[114:115], v114
	v_mul_f64 v[124:125], v[114:115], s[14:15]
	v_floor_f64_e32 v[124:125], v[124:125]
	v_fma_f64 v[114:115], v[114:115], s[14:15], -v[124:125]
	v_cvt_f32_f64_e32 v115, v[114:115]
	v_sin_f32_e32 v114, v115
	v_cos_f32_e32 v124, v115
	v_mul_f32_e32 v115, v211, v226
	v_cvt_f64_f32_e32 v[206:207], v115
	v_mul_f64 v[240:241], v[206:207], s[14:15]
	v_floor_f64_e32 v[240:241], v[240:241]
	v_fma_f64 v[206:207], v[206:207], s[14:15], -v[240:241]
	v_cvt_f32_f64_e32 v125, v[206:207]
	v_sin_f32_e32 v115, v125
	v_cos_f32_e32 v125, v125
	v_cvt_pk_bf16_f32 v123, v116, v117
	v_pk_mul_f32 v[206:207], v[126:127], v[114:115]
	s_nop 0
	v_pk_fma_f32 v[206:207], v[118:119], v[124:125], v[206:207] neg_lo:[0,0,1] neg_hi:[0,0,1]
	v_pk_mul_f32 v[124:125], v[126:127], v[124:125]
	s_nop 0
	v_pk_fma_f32 v[118:119], v[118:119], v[114:115], v[124:125]
	v_mul_f32_e32 v114, v209, v226
	v_cvt_f64_f32_e32 v[114:115], v114
	v_mul_f64 v[124:125], v[114:115], s[14:15]
	v_floor_f64_e32 v[124:125], v[124:125]
	v_fma_f64 v[114:115], v[114:115], s[14:15], -v[124:125]
	v_cvt_f32_f64_e32 v115, v[114:115]
	v_sin_f32_e32 v114, v115
	v_cos_f32_e32 v124, v115
	v_mul_f32_e32 v115, v208, v226
	v_cvt_f64_f32_e32 v[126:127], v115
	v_mul_f64 v[240:241], v[126:127], s[14:15]
	v_floor_f64_e32 v[240:241], v[240:241]
	v_fma_f64 v[126:127], v[126:127], s[14:15], -v[240:241]
	v_cvt_f32_f64_e32 v125, v[126:127]
	v_sin_f32_e32 v115, v125
	v_cos_f32_e32 v125, v125
	v_cvt_pk_bf16_f32 v116, v118, v119
	v_pk_mul_f32 v[126:127], v[128:129], v[114:115]
	s_nop 0
	v_pk_fma_f32 v[126:127], v[120:121], v[124:125], v[126:127] neg_lo:[0,0,1] neg_hi:[0,0,1]
	v_pk_mul_f32 v[124:125], v[128:129], v[124:125]
	v_cvt_pk_bf16_f32 v129, v236, v237
	v_pk_fma_f32 v[120:121], v[120:121], v[114:115], v[124:125]
	v_or_b32_e32 v115, v194, v189
	v_mul_lo_u32 v128, v115, v179
	v_mul_lo_u32 v114, v195, v178
	v_mad_u64_u32 v[124:125], s[12:13], v115, v178, 0
	v_add3_u32 v125, v125, v128, v114
	v_lshl_add_u64 v[124:125], v[124:125], 1, v[180:181]
	v_cvt_pk_bf16_f32 v128, v238, v239
	v_cvt_pk_bf16_f32 v117, v120, v121
	v_or_b32_e32 v115, 32, v194
	global_store_dwordx2 v[124:125], v[128:129], off
	v_cvt_pk_bf16_f32 v128, v206, v207
	v_cvt_pk_bf16_f32 v129, v126, v127
	global_store_dwordx2 v[124:125], v[116:117], off offset:48
	v_and_or_b32 v116, v115, s1, v189
	global_store_dwordx2 v[124:125], v[128:129], off offset:16
	global_store_dwordx2 v[124:125], v[122:123], off offset:32
	v_cvt_f32_u32_e32 v124, v116
	s_movk_i32 s1, 0x1fc0
	v_mul_f32_e32 v116, v217, v124
	v_cvt_f64_f32_e32 v[116:117], v116
	v_mul_f64 v[118:119], v[116:117], s[14:15]
	v_floor_f64_e32 v[118:119], v[118:119]
	v_fma_f64 v[116:117], v[116:117], s[14:15], -v[118:119]
	v_cvt_f32_f64_e32 v117, v[116:117]
	v_sin_f32_e32 v116, v117
	v_cos_f32_e32 v118, v117
	v_mul_f32_e32 v117, v218, v124
	v_cvt_f64_f32_e32 v[120:121], v117
	v_mul_f64 v[122:123], v[120:121], s[14:15]
	v_floor_f64_e32 v[122:123], v[122:123]
	v_fma_f64 v[120:121], v[120:121], s[14:15], -v[122:123]
	v_cvt_f32_f64_e32 v119, v[120:121]
	v_sin_f32_e32 v117, v119
	v_cos_f32_e32 v119, v119
	v_pk_mul_f32 v[120:121], v[106:107], v[116:117]
	v_pk_mul_f32 v[106:107], v[106:107], v[118:119]
	v_pk_fma_f32 v[120:121], v[98:99], v[118:119], v[120:121] neg_lo:[0,0,1] neg_hi:[0,0,1]
	v_pk_fma_f32 v[98:99], v[98:99], v[116:117], v[106:107]
	v_mul_f32_e32 v106, v216, v124
	v_cvt_f64_f32_e32 v[106:107], v106
	v_mul_f64 v[116:117], v[106:107], s[14:15]
	v_floor_f64_e32 v[116:117], v[116:117]
	v_fma_f64 v[106:107], v[106:107], s[14:15], -v[116:117]
	v_cvt_f32_f64_e32 v107, v[106:107]
	v_sin_f32_e32 v106, v107
	v_cos_f32_e32 v116, v107
	v_mul_f32_e32 v107, v215, v124
	v_cvt_f64_f32_e32 v[118:119], v107
	v_mul_f64 v[122:123], v[118:119], s[14:15]
	v_floor_f64_e32 v[122:123], v[122:123]
	v_fma_f64 v[118:119], v[118:119], s[14:15], -v[122:123]
	v_cvt_f32_f64_e32 v117, v[118:119]
	v_sin_f32_e32 v107, v117
	v_cos_f32_e32 v117, v117
	v_cvt_pk_bf16_f32 v98, v98, v99
	v_pk_mul_f32 v[118:119], v[108:109], v[106:107]
	v_pk_mul_f32 v[108:109], v[108:109], v[116:117]
	v_pk_fma_f32 v[118:119], v[100:101], v[116:117], v[118:119] neg_lo:[0,0,1] neg_hi:[0,0,1]
	v_pk_fma_f32 v[100:101], v[100:101], v[106:107], v[108:109]
	v_mul_f32_e32 v106, v213, v124
	v_cvt_f64_f32_e32 v[106:107], v106
	v_mul_f64 v[108:109], v[106:107], s[14:15]
	v_floor_f64_e32 v[108:109], v[108:109]
	v_fma_f64 v[106:107], v[106:107], s[14:15], -v[108:109]
	v_cvt_f32_f64_e32 v107, v[106:107]
	v_sin_f32_e32 v106, v107
	v_cos_f32_e32 v108, v107
	v_mul_f32_e32 v107, v211, v124
	v_cvt_f64_f32_e32 v[116:117], v107
	v_mul_f64 v[122:123], v[116:117], s[14:15]
	v_floor_f64_e32 v[122:123], v[122:123]
	v_fma_f64 v[116:117], v[116:117], s[14:15], -v[122:123]
	v_cvt_f32_f64_e32 v109, v[116:117]
	v_sin_f32_e32 v107, v109
	v_cos_f32_e32 v109, v109
	v_cvt_pk_bf16_f32 v99, v100, v101
	v_pk_mul_f32 v[116:117], v[110:111], v[106:107]
	s_nop 0
	v_pk_fma_f32 v[116:117], v[102:103], v[108:109], v[116:117] neg_lo:[0,0,1] neg_hi:[0,0,1]
	v_pk_mul_f32 v[108:109], v[110:111], v[108:109]
	s_nop 0
	v_pk_fma_f32 v[102:103], v[102:103], v[106:107], v[108:109]
	v_mul_f32_e32 v106, v209, v124
	v_cvt_f64_f32_e32 v[106:107], v106
	v_mul_f64 v[108:109], v[106:107], s[14:15]
	v_floor_f64_e32 v[108:109], v[108:109]
	v_fma_f64 v[106:107], v[106:107], s[14:15], -v[108:109]
	v_cvt_f32_f64_e32 v107, v[106:107]
	v_sin_f32_e32 v106, v107
	v_cos_f32_e32 v108, v107
	v_mul_f32_e32 v107, v208, v124
	v_cvt_f64_f32_e32 v[110:111], v107
	v_mul_f64 v[122:123], v[110:111], s[14:15]
	v_floor_f64_e32 v[122:123], v[122:123]
	v_fma_f64 v[110:111], v[110:111], s[14:15], -v[122:123]
	v_cvt_f32_f64_e32 v109, v[110:111]
	v_sin_f32_e32 v107, v109
	v_cos_f32_e32 v109, v109
	v_pk_mul_f32 v[110:111], v[112:113], v[106:107]
	s_nop 0
	v_pk_fma_f32 v[110:111], v[104:105], v[108:109], v[110:111] neg_lo:[0,0,1] neg_hi:[0,0,1]
	v_pk_mul_f32 v[108:109], v[112:113], v[108:109]
	s_nop 0
	v_pk_fma_f32 v[104:105], v[104:105], v[106:107], v[108:109]
	v_or_b32_e32 v106, v115, v189
	v_mul_lo_u32 v108, v106, v179
	v_mad_u64_u32 v[106:107], s[12:13], v106, v178, 0
	v_add3_u32 v107, v107, v108, v114
	v_lshl_add_u64 v[106:107], v[106:107], 1, v[180:181]
	v_cvt_pk_bf16_f32 v108, v120, v121
	v_cvt_pk_bf16_f32 v109, v118, v119
	global_store_dwordx2 v[106:107], v[108:109], off
	v_cvt_pk_bf16_f32 v108, v116, v117
	v_cvt_pk_bf16_f32 v109, v110, v111
	global_store_dwordx2 v[106:107], v[98:99], off offset:32
	v_cvt_pk_bf16_f32 v98, v102, v103
	v_cvt_pk_bf16_f32 v99, v104, v105
	global_store_dwordx2 v[106:107], v[108:109], off offset:16
	global_store_dwordx2 v[106:107], v[98:99], off offset:48
	v_or_b32_e32 v106, 64, v194
	v_and_or_b32 v98, v106, s1, v189
	v_cvt_f32_u32_e32 v107, v98
	s_movk_i32 s1, 0x1fe0
	v_mul_f32_e32 v98, v217, v107
	v_cvt_f64_f32_e32 v[98:99], v98
	v_mul_f64 v[100:101], v[98:99], s[14:15]
	v_floor_f64_e32 v[100:101], v[100:101]
	v_fma_f64 v[98:99], v[98:99], s[14:15], -v[100:101]
	v_cvt_f32_f64_e32 v99, v[98:99]
	v_sin_f32_e32 v98, v99
	v_cos_f32_e32 v100, v99
	v_mul_f32_e32 v99, v218, v107
	v_cvt_f64_f32_e32 v[102:103], v99
	v_mul_f64 v[104:105], v[102:103], s[14:15]
	v_floor_f64_e32 v[104:105], v[104:105]
	v_fma_f64 v[102:103], v[102:103], s[14:15], -v[104:105]
	v_cvt_f32_f64_e32 v101, v[102:103]
	v_sin_f32_e32 v99, v101
	v_cos_f32_e32 v101, v101
	v_pk_mul_f32 v[102:103], v[90:91], v[98:99]
	v_pk_mul_f32 v[90:91], v[90:91], v[100:101]
	v_pk_fma_f32 v[102:103], v[82:83], v[100:101], v[102:103] neg_lo:[0,0,1] neg_hi:[0,0,1]
	v_pk_fma_f32 v[82:83], v[82:83], v[98:99], v[90:91]
	v_mul_f32_e32 v90, v216, v107
	v_cvt_f64_f32_e32 v[90:91], v90
	v_mul_f64 v[98:99], v[90:91], s[14:15]
	v_floor_f64_e32 v[98:99], v[98:99]
	v_fma_f64 v[90:91], v[90:91], s[14:15], -v[98:99]
	v_cvt_f32_f64_e32 v91, v[90:91]
	v_sin_f32_e32 v90, v91
	v_cos_f32_e32 v98, v91
	v_mul_f32_e32 v91, v215, v107
	v_cvt_f64_f32_e32 v[100:101], v91
	v_mul_f64 v[104:105], v[100:101], s[14:15]
	v_floor_f64_e32 v[104:105], v[104:105]
	v_fma_f64 v[100:101], v[100:101], s[14:15], -v[104:105]
	v_cvt_f32_f64_e32 v99, v[100:101]
	v_sin_f32_e32 v91, v99
	v_cos_f32_e32 v99, v99
	v_cvt_pk_bf16_f32 v82, v82, v83
	v_pk_mul_f32 v[100:101], v[92:93], v[90:91]
	v_pk_mul_f32 v[92:93], v[92:93], v[98:99]
	v_pk_fma_f32 v[100:101], v[84:85], v[98:99], v[100:101] neg_lo:[0,0,1] neg_hi:[0,0,1]
	v_pk_fma_f32 v[84:85], v[84:85], v[90:91], v[92:93]
	v_mul_f32_e32 v90, v213, v107
	v_cvt_f64_f32_e32 v[90:91], v90
	v_mul_f64 v[92:93], v[90:91], s[14:15]
	v_floor_f64_e32 v[92:93], v[92:93]
	v_fma_f64 v[90:91], v[90:91], s[14:15], -v[92:93]
	v_cvt_f32_f64_e32 v91, v[90:91]
	v_sin_f32_e32 v90, v91
	v_cos_f32_e32 v92, v91
	v_mul_f32_e32 v91, v211, v107
	v_cvt_f64_f32_e32 v[98:99], v91
	v_mul_f64 v[104:105], v[98:99], s[14:15]
	v_floor_f64_e32 v[104:105], v[104:105]
	v_fma_f64 v[98:99], v[98:99], s[14:15], -v[104:105]
	v_cvt_f32_f64_e32 v93, v[98:99]
	v_sin_f32_e32 v91, v93
	v_cos_f32_e32 v93, v93
	v_cvt_pk_bf16_f32 v83, v84, v85
	v_pk_mul_f32 v[98:99], v[94:95], v[90:91]
	s_nop 0
	v_pk_fma_f32 v[98:99], v[86:87], v[92:93], v[98:99] neg_lo:[0,0,1] neg_hi:[0,0,1]
	v_pk_mul_f32 v[92:93], v[94:95], v[92:93]
	s_nop 0
	v_pk_fma_f32 v[86:87], v[86:87], v[90:91], v[92:93]
	v_mul_f32_e32 v90, v209, v107
	v_cvt_f64_f32_e32 v[90:91], v90
	v_mul_f64 v[92:93], v[90:91], s[14:15]
	v_floor_f64_e32 v[92:93], v[92:93]
	v_fma_f64 v[90:91], v[90:91], s[14:15], -v[92:93]
	v_cvt_f32_f64_e32 v91, v[90:91]
	v_sin_f32_e32 v90, v91
	v_cos_f32_e32 v92, v91
	v_mul_f32_e32 v91, v208, v107
	v_cvt_f64_f32_e32 v[94:95], v91
	v_mul_f64 v[104:105], v[94:95], s[14:15]
	v_floor_f64_e32 v[104:105], v[104:105]
	v_fma_f64 v[94:95], v[94:95], s[14:15], -v[104:105]
	v_cvt_f32_f64_e32 v93, v[94:95]
	v_sin_f32_e32 v91, v93
	v_cos_f32_e32 v93, v93
	v_pk_mul_f32 v[94:95], v[96:97], v[90:91]
	s_nop 0
	v_pk_fma_f32 v[94:95], v[88:89], v[92:93], v[94:95] neg_lo:[0,0,1] neg_hi:[0,0,1]
	v_pk_mul_f32 v[92:93], v[96:97], v[92:93]
	s_nop 0
	v_pk_fma_f32 v[88:89], v[88:89], v[90:91], v[92:93]
	v_or_b32_e32 v90, v106, v189
	v_mul_lo_u32 v92, v90, v179
	v_mad_u64_u32 v[90:91], s[12:13], v90, v178, 0
	v_add3_u32 v91, v91, v92, v114
	v_lshl_add_u64 v[90:91], v[90:91], 1, v[180:181]
	v_cvt_pk_bf16_f32 v92, v102, v103
	v_cvt_pk_bf16_f32 v93, v100, v101
	global_store_dwordx2 v[90:91], v[92:93], off
	v_cvt_pk_bf16_f32 v92, v98, v99
	v_cvt_pk_bf16_f32 v93, v94, v95
	global_store_dwordx2 v[90:91], v[82:83], off offset:32
	v_cvt_pk_bf16_f32 v82, v86, v87
	v_cvt_pk_bf16_f32 v83, v88, v89
	global_store_dwordx2 v[90:91], v[92:93], off offset:16
	global_store_dwordx2 v[90:91], v[82:83], off offset:48
	v_or_b32_e32 v90, 0x60, v194
	v_and_or_b32 v82, v90, s1, v189
	v_cvt_f32_u32_e32 v91, v82
	v_mul_f32_e32 v82, v217, v91
	v_cvt_f64_f32_e32 v[82:83], v82
	v_mul_f64 v[84:85], v[82:83], s[14:15]
	v_floor_f64_e32 v[84:85], v[84:85]
	v_fma_f64 v[82:83], v[82:83], s[14:15], -v[84:85]
	v_cvt_f32_f64_e32 v83, v[82:83]
	v_sin_f32_e32 v82, v83
	v_cos_f32_e32 v84, v83
	v_mul_f32_e32 v83, v218, v91
	v_cvt_f64_f32_e32 v[86:87], v83
	v_mul_f64 v[88:89], v[86:87], s[14:15]
	v_floor_f64_e32 v[88:89], v[88:89]
	v_fma_f64 v[86:87], v[86:87], s[14:15], -v[88:89]
	v_cvt_f32_f64_e32 v85, v[86:87]
	v_sin_f32_e32 v83, v85
	v_cos_f32_e32 v85, v85
	v_pk_mul_f32 v[86:87], v[74:75], v[82:83]
	v_pk_mul_f32 v[74:75], v[74:75], v[84:85]
	v_pk_fma_f32 v[86:87], v[66:67], v[84:85], v[86:87] neg_lo:[0,0,1] neg_hi:[0,0,1]
	v_pk_fma_f32 v[66:67], v[66:67], v[82:83], v[74:75]
	v_mul_f32_e32 v74, v216, v91
	v_cvt_f64_f32_e32 v[74:75], v74
	v_mul_f64 v[82:83], v[74:75], s[14:15]
	v_floor_f64_e32 v[82:83], v[82:83]
	v_fma_f64 v[74:75], v[74:75], s[14:15], -v[82:83]
	v_cvt_f32_f64_e32 v75, v[74:75]
	v_sin_f32_e32 v74, v75
	v_cos_f32_e32 v82, v75
	v_mul_f32_e32 v75, v215, v91
	v_cvt_f64_f32_e32 v[84:85], v75
	v_mul_f64 v[88:89], v[84:85], s[14:15]
	v_floor_f64_e32 v[88:89], v[88:89]
	v_fma_f64 v[84:85], v[84:85], s[14:15], -v[88:89]
	v_cvt_f32_f64_e32 v83, v[84:85]
	v_sin_f32_e32 v75, v83
	v_cos_f32_e32 v83, v83
	v_cvt_pk_bf16_f32 v66, v66, v67
	v_pk_mul_f32 v[84:85], v[76:77], v[74:75]
	v_pk_mul_f32 v[76:77], v[76:77], v[82:83]
	v_pk_fma_f32 v[84:85], v[68:69], v[82:83], v[84:85] neg_lo:[0,0,1] neg_hi:[0,0,1]
	v_pk_fma_f32 v[68:69], v[68:69], v[74:75], v[76:77]
	v_mul_f32_e32 v74, v213, v91
	v_cvt_f64_f32_e32 v[74:75], v74
	v_mul_f64 v[76:77], v[74:75], s[14:15]
	v_floor_f64_e32 v[76:77], v[76:77]
	v_fma_f64 v[74:75], v[74:75], s[14:15], -v[76:77]
	v_cvt_f32_f64_e32 v75, v[74:75]
	v_sin_f32_e32 v74, v75
	v_cos_f32_e32 v76, v75
	v_mul_f32_e32 v75, v211, v91
	v_cvt_f64_f32_e32 v[82:83], v75
	v_mul_f64 v[88:89], v[82:83], s[14:15]
	v_floor_f64_e32 v[88:89], v[88:89]
	v_fma_f64 v[82:83], v[82:83], s[14:15], -v[88:89]
	v_cvt_f32_f64_e32 v77, v[82:83]
	v_sin_f32_e32 v75, v77
	v_cos_f32_e32 v77, v77
	v_cvt_pk_bf16_f32 v67, v68, v69
	v_pk_mul_f32 v[82:83], v[78:79], v[74:75]
	s_nop 0
	v_pk_fma_f32 v[82:83], v[70:71], v[76:77], v[82:83] neg_lo:[0,0,1] neg_hi:[0,0,1]
	v_pk_mul_f32 v[76:77], v[78:79], v[76:77]
	s_nop 0
	v_pk_fma_f32 v[70:71], v[70:71], v[74:75], v[76:77]
	v_mul_f32_e32 v74, v209, v91
	v_cvt_f64_f32_e32 v[74:75], v74
	v_mul_f64 v[76:77], v[74:75], s[14:15]
	v_floor_f64_e32 v[76:77], v[76:77]
	v_fma_f64 v[74:75], v[74:75], s[14:15], -v[76:77]
	v_cvt_f32_f64_e32 v75, v[74:75]
	v_sin_f32_e32 v74, v75
	v_cos_f32_e32 v76, v75
	v_mul_f32_e32 v75, v208, v91
	v_cvt_f64_f32_e32 v[78:79], v75
	v_mul_f64 v[88:89], v[78:79], s[14:15]
	v_floor_f64_e32 v[88:89], v[88:89]
	v_fma_f64 v[78:79], v[78:79], s[14:15], -v[88:89]
	v_cvt_f32_f64_e32 v77, v[78:79]
	v_sin_f32_e32 v75, v77
	v_cos_f32_e32 v77, v77
	v_pk_mul_f32 v[78:79], v[80:81], v[74:75]
	s_nop 0
	v_pk_fma_f32 v[78:79], v[72:73], v[76:77], v[78:79] neg_lo:[0,0,1] neg_hi:[0,0,1]
	v_pk_mul_f32 v[76:77], v[80:81], v[76:77]
	s_nop 0
	v_pk_fma_f32 v[72:73], v[72:73], v[74:75], v[76:77]
	v_or_b32_e32 v74, v90, v189
	v_mul_lo_u32 v76, v74, v179
	v_mad_u64_u32 v[74:75], s[12:13], v74, v178, 0
	v_add3_u32 v75, v75, v76, v114
	v_lshl_add_u64 v[74:75], v[74:75], 1, v[180:181]
	v_cvt_pk_bf16_f32 v76, v86, v87
	v_cvt_pk_bf16_f32 v77, v84, v85
	global_store_dwordx2 v[74:75], v[76:77], off
	v_cvt_pk_bf16_f32 v76, v82, v83
	v_cvt_pk_bf16_f32 v77, v78, v79
	global_store_dwordx2 v[74:75], v[66:67], off offset:32
	v_cvt_pk_bf16_f32 v66, v70, v71
	v_cvt_pk_bf16_f32 v67, v72, v73
	global_store_dwordx2 v[74:75], v[76:77], off offset:16
	global_store_dwordx2 v[74:75], v[66:67], off offset:48

.LBB0_807:
	s_mul_i32 s3, s9, s82
	s_add_i32 s3, s3, s63
	s_ashr_i32 s5, s3, 31
	s_lshr_b32 s5, s5, 28
	s_add_i32 s5, s3, s5
	s_ashr_i32 s10, s5, 4
	s_and_b32 s5, s5, -16
	s_sub_i32 s3, s3, s5
	s_lshl_b32 s5, s10, 1
	s_and_b32 s10, s3, 1
	s_or_b32 s5, s10, s5
	v_readlane_b32 s10, v252, 35
	s_sub_i32 s12, 0x7f, s5
	v_readlane_b32 s11, v252, 36
	s_and_b64 s[10:11], s[10:11], exec
	s_cselect_b32 s10, s12, s5
	v_mov_b32_e32 v0, v222
	s_ashr_i32 s11, s10, 31
	v_and_b32_e32 v190, 0xffffff80, v0
	s_lshl_b64 s[10:11], s[10:11], 8
	v_ashrrev_i32_e32 v191, 31, v190
	v_lshl_add_u64 v[190:191], s[10:11], 0, v[190:191]
	s_lshl_b32 s3, s3, 6
	v_and_b32_e32 v185, 64, v0
	v_and_or_b32 v190, v0, 31, v190
	s_and_b32 s3, s3, 0xffffff80
	v_lshrrev_b32_e32 v0, 3, v0
	s_ashr_i32 s5, s3, 31
	v_and_b32_e32 v0, 4, v0
	v_or3_b32 v192, v0, v185, s3
	v_mov_b32_e32 v193, s5
	v_lshlrev_b64 v[190:191], 10, v[190:191]
	v_lshl_add_u64 v[190:191], v[190:191], 0, v[192:193]
	v_lshlrev_b64 v[190:191], 2, v[190:191]
	v_lshl_add_u64 v[196:197], s[0:1], 0, v[190:191]
	s_mov_b64 s[98:99], 0x20000
	v_readlane_b32 s12, v252, 31
	v_readlane_b32 s13, v252, 32
	v_lshl_add_u64 v[220:221], s[12:13], 0, v[190:191]
	v_lshl_add_u64 v[192:193], v[196:197], 0, 0
	global_load_dwordx4 v[194:197], v[192:193], off
	global_load_dwordx4 v[198:201], v[192:193], off offset:32
	global_load_dwordx4 v[202:205], v[192:193], off offset:64
	global_load_dwordx4 v[206:209], v[192:193], off offset:96
	global_load_dwordx4 v[216:219], v[192:193], off offset:128
	global_load_dwordx4 v[236:239], v[192:193], off offset:160
	global_load_dwordx4 v[240:243], v[192:193], off offset:192
	global_load_dwordx4 v[244:247], v[192:193], off offset:224
	s_waitcnt vmcnt(7)
	v_pk_fma_f32 v[98:99], v[98:99], 0.5, v[194:195] op_sel_hi:[1,0,1]
	v_pk_fma_f32 v[100:101], v[100:101], 0.5, v[196:197] op_sel_hi:[1,0,1]
	global_store_dwordx4 v[220:221], v[98:101], off
	v_lshl_add_u64 v[192:193], v[192:193], 0, s[98:99]
	global_load_dwordx4 v[194:197], v[192:193], off
	s_waitcnt vmcnt(8)
	v_pk_fma_f32 v[102:103], v[102:103], 0.5, v[198:199] op_sel_hi:[1,0,1]
	v_pk_fma_f32 v[104:105], v[104:105], 0.5, v[200:201] op_sel_hi:[1,0,1]
	global_store_dwordx4 v[220:221], v[102:105], off offset:32
	global_load_dwordx4 v[198:201], v[192:193], off offset:32
	s_waitcnt vmcnt(9)
	v_pk_fma_f32 v[106:107], v[106:107], 0.5, v[202:203] op_sel_hi:[1,0,1]
	v_pk_fma_f32 v[108:109], v[108:109], 0.5, v[204:205] op_sel_hi:[1,0,1]
	global_store_dwordx4 v[220:221], v[106:109], off offset:64
	global_load_dwordx4 v[202:205], v[192:193], off offset:64
	s_waitcnt vmcnt(10)
	v_pk_fma_f32 v[110:111], v[110:111], 0.5, v[206:207] op_sel_hi:[1,0,1]
	v_pk_fma_f32 v[112:113], v[112:113], 0.5, v[208:209] op_sel_hi:[1,0,1]
	global_store_dwordx4 v[220:221], v[110:113], off offset:96
	global_load_dwordx4 v[206:209], v[192:193], off offset:96
	s_waitcnt vmcnt(11)
	v_pk_fma_f32 v[114:115], v[114:115], 0.5, v[216:217] op_sel_hi:[1,0,1]
	v_pk_fma_f32 v[116:117], v[116:117], 0.5, v[218:219] op_sel_hi:[1,0,1]
	global_store_dwordx4 v[220:221], v[114:117], off offset:128
	global_load_dwordx4 v[216:219], v[192:193], off offset:128
	s_waitcnt vmcnt(12)
	v_pk_fma_f32 v[118:119], v[118:119], 0.5, v[236:237] op_sel_hi:[1,0,1]
	v_pk_fma_f32 v[120:121], v[120:121], 0.5, v[238:239] op_sel_hi:[1,0,1]
	global_store_dwordx4 v[220:221], v[118:121], off offset:160
	global_load_dwordx4 v[236:239], v[192:193], off offset:160
	s_waitcnt vmcnt(13)
	v_pk_fma_f32 v[122:123], v[122:123], 0.5, v[240:241] op_sel_hi:[1,0,1]
	v_pk_fma_f32 v[124:125], v[124:125], 0.5, v[242:243] op_sel_hi:[1,0,1]
	global_store_dwordx4 v[220:221], v[122:125], off offset:192
	global_load_dwordx4 v[240:243], v[192:193], off offset:192
	s_waitcnt vmcnt(14)
	v_pk_fma_f32 v[126:127], v[126:127], 0.5, v[244:245] op_sel_hi:[1,0,1]
	v_pk_fma_f32 v[128:129], v[128:129], 0.5, v[246:247] op_sel_hi:[1,0,1]
	global_store_dwordx4 v[220:221], v[126:129], off offset:224
	global_load_dwordx4 v[244:247], v[192:193], off offset:224
	s_waitcnt vmcnt(14)
	v_pk_fma_f32 v[82:83], v[82:83], 0.5, v[194:195] op_sel_hi:[1,0,1]
	v_pk_fma_f32 v[84:85], v[84:85], 0.5, v[196:197] op_sel_hi:[1,0,1]
	v_lshl_add_u64 v[220:221], v[220:221], 0, s[98:99]
	global_store_dwordx4 v[220:221], v[82:85], off
	v_lshl_add_u64 v[192:193], v[192:193], 0, s[98:99]
	global_load_dwordx4 v[194:197], v[192:193], off
	s_waitcnt vmcnt(14)
	v_pk_fma_f32 v[86:87], v[86:87], 0.5, v[198:199] op_sel_hi:[1,0,1]
	v_pk_fma_f32 v[88:89], v[88:89], 0.5, v[200:201] op_sel_hi:[1,0,1]
	global_store_dwordx4 v[220:221], v[86:89], off offset:32
	global_load_dwordx4 v[198:201], v[192:193], off offset:32
	s_waitcnt vmcnt(14)
	v_pk_fma_f32 v[90:91], v[90:91], 0.5, v[202:203] op_sel_hi:[1,0,1]
	v_pk_fma_f32 v[92:93], v[92:93], 0.5, v[204:205] op_sel_hi:[1,0,1]
	global_store_dwordx4 v[220:221], v[90:93], off offset:64
	global_load_dwordx4 v[202:205], v[192:193], off offset:64
	s_waitcnt vmcnt(14)
	v_pk_fma_f32 v[94:95], v[94:95], 0.5, v[206:207] op_sel_hi:[1,0,1]
	v_pk_fma_f32 v[96:97], v[96:97], 0.5, v[208:209] op_sel_hi:[1,0,1]
	global_store_dwordx4 v[220:221], v[94:97], off offset:96
	global_load_dwordx4 v[206:209], v[192:193], off offset:96
	s_waitcnt vmcnt(14)
	v_pk_fma_f32 v[66:67], v[66:67], 0.5, v[216:217] op_sel_hi:[1,0,1]
	v_pk_fma_f32 v[68:69], v[68:69], 0.5, v[218:219] op_sel_hi:[1,0,1]
	global_store_dwordx4 v[220:221], v[66:69], off offset:128
	global_load_dwordx4 v[216:219], v[192:193], off offset:128
	s_waitcnt vmcnt(14)
	v_pk_fma_f32 v[70:71], v[70:71], 0.5, v[236:237] op_sel_hi:[1,0,1]
	v_pk_fma_f32 v[72:73], v[72:73], 0.5, v[238:239] op_sel_hi:[1,0,1]
	global_store_dwordx4 v[220:221], v[70:73], off offset:160
	global_load_dwordx4 v[236:239], v[192:193], off offset:160
	s_waitcnt vmcnt(14)
	v_pk_fma_f32 v[74:75], v[74:75], 0.5, v[240:241] op_sel_hi:[1,0,1]
	v_pk_fma_f32 v[76:77], v[76:77], 0.5, v[242:243] op_sel_hi:[1,0,1]
	global_store_dwordx4 v[220:221], v[74:77], off offset:192
	global_load_dwordx4 v[240:243], v[192:193], off offset:192
	s_waitcnt vmcnt(14)
	v_pk_fma_f32 v[78:79], v[78:79], 0.5, v[244:245] op_sel_hi:[1,0,1]
	v_pk_fma_f32 v[80:81], v[80:81], 0.5, v[246:247] op_sel_hi:[1,0,1]
	global_store_dwordx4 v[220:221], v[78:81], off offset:224
	global_load_dwordx4 v[244:247], v[192:193], off offset:224
	s_waitcnt vmcnt(14)
	v_pk_fma_f32 v[50:51], v[50:51], 0.5, v[194:195] op_sel_hi:[1,0,1]
	v_pk_fma_f32 v[52:53], v[52:53], 0.5, v[196:197] op_sel_hi:[1,0,1]
	v_lshl_add_u64 v[220:221], v[220:221], 0, s[98:99]
	global_store_dwordx4 v[220:221], v[50:53], off
	v_lshl_add_u64 v[192:193], v[192:193], 0, s[98:99]
	global_load_dwordx4 v[194:197], v[192:193], off
	s_waitcnt vmcnt(14)
	v_pk_fma_f32 v[54:55], v[54:55], 0.5, v[198:199] op_sel_hi:[1,0,1]
	v_pk_fma_f32 v[56:57], v[56:57], 0.5, v[200:201] op_sel_hi:[1,0,1]
	global_store_dwordx4 v[220:221], v[54:57], off offset:32
	global_load_dwordx4 v[198:201], v[192:193], off offset:32
	s_waitcnt vmcnt(14)
	v_pk_fma_f32 v[58:59], v[58:59], 0.5, v[202:203] op_sel_hi:[1,0,1]
	v_pk_fma_f32 v[60:61], v[60:61], 0.5, v[204:205] op_sel_hi:[1,0,1]
	global_store_dwordx4 v[220:221], v[58:61], off offset:64
	global_load_dwordx4 v[202:205], v[192:193], off offset:64
	s_waitcnt vmcnt(14)
	v_pk_fma_f32 v[62:63], v[62:63], 0.5, v[206:207] op_sel_hi:[1,0,1]
	v_pk_fma_f32 v[64:65], v[64:65], 0.5, v[208:209] op_sel_hi:[1,0,1]
	global_store_dwordx4 v[220:221], v[62:65], off offset:96
	global_load_dwordx4 v[206:209], v[192:193], off offset:96
	s_waitcnt vmcnt(14)
	v_pk_fma_f32 v[34:35], v[34:35], 0.5, v[216:217] op_sel_hi:[1,0,1]
	v_pk_fma_f32 v[36:37], v[36:37], 0.5, v[218:219] op_sel_hi:[1,0,1]
	global_store_dwordx4 v[220:221], v[34:37], off offset:128
	global_load_dwordx4 v[216:219], v[192:193], off offset:128
	s_waitcnt vmcnt(14)
	v_pk_fma_f32 v[38:39], v[38:39], 0.5, v[236:237] op_sel_hi:[1,0,1]
	v_pk_fma_f32 v[40:41], v[40:41], 0.5, v[238:239] op_sel_hi:[1,0,1]
	global_store_dwordx4 v[220:221], v[38:41], off offset:160
	global_load_dwordx4 v[236:239], v[192:193], off offset:160
	s_waitcnt vmcnt(14)
	v_pk_fma_f32 v[42:43], v[42:43], 0.5, v[240:241] op_sel_hi:[1,0,1]
	v_pk_fma_f32 v[44:45], v[44:45], 0.5, v[242:243] op_sel_hi:[1,0,1]
	global_store_dwordx4 v[220:221], v[42:45], off offset:192
	global_load_dwordx4 v[240:243], v[192:193], off offset:192
	s_waitcnt vmcnt(14)
	v_pk_fma_f32 v[46:47], v[46:47], 0.5, v[244:245] op_sel_hi:[1,0,1]
	v_pk_fma_f32 v[48:49], v[48:49], 0.5, v[246:247] op_sel_hi:[1,0,1]
	global_store_dwordx4 v[220:221], v[46:49], off offset:224
	global_load_dwordx4 v[244:247], v[192:193], off offset:224
	s_waitcnt vmcnt(14)
	v_pk_fma_f32 v[18:19], v[18:19], 0.5, v[194:195] op_sel_hi:[1,0,1]
	v_pk_fma_f32 v[20:21], v[20:21], 0.5, v[196:197] op_sel_hi:[1,0,1]
	v_lshl_add_u64 v[220:221], v[220:221], 0, s[98:99]
	global_store_dwordx4 v[220:221], v[18:21], off
	s_waitcnt vmcnt(13)
	v_pk_fma_f32 v[22:23], v[22:23], 0.5, v[198:199] op_sel_hi:[1,0,1]
	v_pk_fma_f32 v[24:25], v[24:25], 0.5, v[200:201] op_sel_hi:[1,0,1]
	global_store_dwordx4 v[220:221], v[22:25], off offset:32
	s_waitcnt vmcnt(12)
	v_pk_fma_f32 v[26:27], v[26:27], 0.5, v[202:203] op_sel_hi:[1,0,1]
	v_pk_fma_f32 v[28:29], v[28:29], 0.5, v[204:205] op_sel_hi:[1,0,1]
	global_store_dwordx4 v[220:221], v[26:29], off offset:64
	s_waitcnt vmcnt(11)
	v_pk_fma_f32 v[30:31], v[30:31], 0.5, v[206:207] op_sel_hi:[1,0,1]
	v_pk_fma_f32 v[32:33], v[32:33], 0.5, v[208:209] op_sel_hi:[1,0,1]
	global_store_dwordx4 v[220:221], v[30:33], off offset:96
	s_waitcnt vmcnt(10)
	v_pk_fma_f32 v[2:3], v[2:3], 0.5, v[216:217] op_sel_hi:[1,0,1]
	v_pk_fma_f32 v[4:5], v[4:5], 0.5, v[218:219] op_sel_hi:[1,0,1]
	global_store_dwordx4 v[220:221], v[2:5], off offset:128
	s_waitcnt vmcnt(9)
	v_pk_fma_f32 v[6:7], v[6:7], 0.5, v[236:237] op_sel_hi:[1,0,1]
	v_pk_fma_f32 v[8:9], v[8:9], 0.5, v[238:239] op_sel_hi:[1,0,1]
	global_store_dwordx4 v[220:221], v[6:9], off offset:160
	s_waitcnt vmcnt(8)
	v_pk_fma_f32 v[10:11], v[10:11], 0.5, v[240:241] op_sel_hi:[1,0,1]
	v_pk_fma_f32 v[12:13], v[12:13], 0.5, v[242:243] op_sel_hi:[1,0,1]
	global_store_dwordx4 v[220:221], v[10:13], off offset:192
	s_waitcnt vmcnt(7)
	v_pk_fma_f32 v[14:15], v[14:15], 0.5, v[244:245] op_sel_hi:[1,0,1]
	v_pk_fma_f32 v[16:17], v[16:17], 0.5, v[246:247] op_sel_hi:[1,0,1]
	global_store_dwordx4 v[220:221], v[14:17], off offset:224
	s_add_i32 s9, s9, 1
	s_mov_b32 s5, 0
	v_mov_b32_e32 v98, 0
	v_mov_b32_e32 v99, 0
	v_mov_b32_e32 v100, 0
	v_mov_b32_e32 v101, 0
	v_mov_b32_e32 v102, 0
	v_mov_b32_e32 v103, 0
	v_mov_b32_e32 v104, 0
	v_mov_b32_e32 v105, 0
	v_mov_b32_e32 v106, 0
	v_mov_b32_e32 v107, 0
	v_mov_b32_e32 v108, 0
	v_mov_b32_e32 v109, 0
	v_mov_b32_e32 v110, 0
	v_mov_b32_e32 v111, 0
	v_mov_b32_e32 v112, 0
	v_mov_b32_e32 v113, 0
	v_mov_b32_e32 v114, 0
	v_mov_b32_e32 v115, 0
	v_mov_b32_e32 v116, 0
	v_mov_b32_e32 v117, 0
	v_mov_b32_e32 v118, 0
	v_mov_b32_e32 v119, 0
	v_mov_b32_e32 v120, 0
	v_mov_b32_e32 v121, 0
	v_mov_b32_e32 v122, 0
	v_mov_b32_e32 v123, 0
	v_mov_b32_e32 v124, 0
	v_mov_b32_e32 v125, 0
	v_mov_b32_e32 v126, 0
	v_mov_b32_e32 v127, 0
	v_mov_b32_e32 v128, 0
	v_mov_b32_e32 v129, 0
	v_mov_b32_e32 v82, 0
	v_mov_b32_e32 v83, 0
	v_mov_b32_e32 v84, 0
	v_mov_b32_e32 v85, 0
	v_mov_b32_e32 v86, 0
	v_mov_b32_e32 v87, 0
	v_mov_b32_e32 v88, 0
	v_mov_b32_e32 v89, 0
	v_mov_b32_e32 v90, 0
	v_mov_b32_e32 v91, 0
	v_mov_b32_e32 v92, 0
	v_mov_b32_e32 v93, 0
	v_mov_b32_e32 v94, 0
	v_mov_b32_e32 v95, 0
	v_mov_b32_e32 v96, 0
	v_mov_b32_e32 v97, 0
	v_mov_b32_e32 v66, 0
	v_mov_b32_e32 v67, 0
	v_mov_b32_e32 v68, 0
	v_mov_b32_e32 v69, 0
	v_mov_b32_e32 v70, 0
	v_mov_b32_e32 v71, 0
	v_mov_b32_e32 v72, 0
	v_mov_b32_e32 v73, 0
	v_mov_b32_e32 v74, 0
	v_mov_b32_e32 v75, 0
	v_mov_b32_e32 v76, 0
	v_mov_b32_e32 v77, 0
	v_mov_b32_e32 v78, 0
	v_mov_b32_e32 v79, 0
	v_mov_b32_e32 v80, 0
	v_mov_b32_e32 v81, 0
	v_mov_b32_e32 v50, 0
	v_mov_b32_e32 v51, 0
	v_mov_b32_e32 v52, 0
	v_mov_b32_e32 v53, 0
	v_mov_b32_e32 v54, 0
	v_mov_b32_e32 v55, 0
	v_mov_b32_e32 v56, 0
	v_mov_b32_e32 v57, 0
	v_mov_b32_e32 v58, 0
	v_mov_b32_e32 v59, 0
	v_mov_b32_e32 v60, 0
	v_mov_b32_e32 v61, 0
	v_mov_b32_e32 v62, 0
	v_mov_b32_e32 v63, 0
	v_mov_b32_e32 v64, 0
	v_mov_b32_e32 v65, 0
	v_mov_b32_e32 v34, 0
	v_mov_b32_e32 v35, 0
	v_mov_b32_e32 v36, 0
	v_mov_b32_e32 v37, 0
	v_mov_b32_e32 v38, 0
	v_mov_b32_e32 v39, 0
	v_mov_b32_e32 v40, 0
	v_mov_b32_e32 v41, 0
	v_mov_b32_e32 v42, 0
	v_mov_b32_e32 v43, 0
	v_mov_b32_e32 v44, 0
	v_mov_b32_e32 v45, 0
	v_mov_b32_e32 v46, 0
	v_mov_b32_e32 v47, 0
	v_mov_b32_e32 v48, 0
	v_mov_b32_e32 v49, 0
	v_mov_b32_e32 v18, 0
	v_mov_b32_e32 v19, 0
	v_mov_b32_e32 v20, 0
	v_mov_b32_e32 v21, 0
	v_mov_b32_e32 v22, 0
	v_mov_b32_e32 v23, 0
	v_mov_b32_e32 v24, 0
	v_mov_b32_e32 v25, 0
	v_mov_b32_e32 v26, 0
	v_mov_b32_e32 v27, 0
	v_mov_b32_e32 v28, 0
	v_mov_b32_e32 v29, 0
	v_mov_b32_e32 v30, 0
	v_mov_b32_e32 v31, 0
	v_mov_b32_e32 v32, 0
	v_mov_b32_e32 v33, 0
	v_mov_b32_e32 v2, 0
	v_mov_b32_e32 v3, 0
	v_mov_b32_e32 v4, 0
	v_mov_b32_e32 v5, 0
	v_mov_b32_e32 v6, 0
	v_mov_b32_e32 v7, 0
	v_mov_b32_e32 v8, 0
	v_mov_b32_e32 v9, 0
	v_mov_b32_e32 v10, 0
	v_mov_b32_e32 v11, 0
	v_mov_b32_e32 v12, 0
	v_mov_b32_e32 v13, 0
	v_mov_b32_e32 v14, 0
	v_mov_b32_e32 v15, 0
	v_mov_b32_e32 v16, 0
	v_mov_b32_e32 v17, 0
	s_cmp_ge_i32 s9, s8
	s_cbranch_scc0 .LBB0_803
